# hgm12 (HGRN M-stage LDS reads issued ahead into a register pool) + saddr LDS-DMA addressing in five GEMM K-loops (72 VALU adds removed per trip set)
# speedup vs baseline: 1.0293x; 1.0030x over previous
.Lpg8skip0:
	s_waitcnt lgkmcnt(0)
	s_barrier
	s_setprio 1
	s_waitcnt lgkmcnt(0)
	v_mfma_f32_16x16x32_bf16 v[124:127], v[156:159], v[188:191], v[124:127]
	v_mfma_f32_16x16x32_bf16 v[120:123], v[164:167], v[188:191], v[120:123]
	v_mfma_f32_16x16x32_bf16 v[108:111], v[156:159], v[196:199], v[108:111]
	v_mfma_f32_16x16x32_bf16 v[104:107], v[164:167], v[196:199], v[104:107]
	v_mfma_f32_16x16x32_bf16 v[92:95], v[156:159], v[204:207], v[92:95]
	v_mfma_f32_16x16x32_bf16 v[88:91], v[164:167], v[204:207], v[88:91]
	v_mfma_f32_16x16x32_bf16 v[76:79], v[156:159], v[216:219], v[76:79]
	v_mfma_f32_16x16x32_bf16 v[72:75], v[164:167], v[216:219], v[72:75]
	v_mfma_f32_16x16x32_bf16 v[124:127], v[160:163], v[192:195], v[124:127]
	v_mfma_f32_16x16x32_bf16 v[120:123], v[168:171], v[192:195], v[120:123]
	v_mfma_f32_16x16x32_bf16 v[108:111], v[160:163], v[200:203], v[108:111]
	v_mfma_f32_16x16x32_bf16 v[104:107], v[168:171], v[200:203], v[104:107]
	v_mfma_f32_16x16x32_bf16 v[92:95], v[160:163], v[212:215], v[92:95]
	v_mfma_f32_16x16x32_bf16 v[88:91], v[168:171], v[212:215], v[88:91]
	v_mfma_f32_16x16x32_bf16 v[76:79], v[160:163], v[220:223], v[76:79]
	v_mfma_f32_16x16x32_bf16 v[72:75], v[168:171], v[220:223], v[72:75]
	s_setprio 0
	s_setprio 1
	v_mfma_f32_16x16x32_bf16 v[116:119], v[172:175], v[188:191], v[116:119]
	v_mfma_f32_16x16x32_bf16 v[112:115], v[180:183], v[188:191], v[112:115]
	v_mfma_f32_16x16x32_bf16 v[100:103], v[172:175], v[196:199], v[100:103]
	v_mfma_f32_16x16x32_bf16 v[96:99], v[180:183], v[196:199], v[96:99]
	v_mfma_f32_16x16x32_bf16 v[84:87], v[172:175], v[204:207], v[84:87]
	v_mfma_f32_16x16x32_bf16 v[80:83], v[180:183], v[204:207], v[80:83]
	v_mfma_f32_16x16x32_bf16 v[68:71], v[172:175], v[216:219], v[68:71]
	v_mfma_f32_16x16x32_bf16 v[64:67], v[180:183], v[216:219], v[64:67]
	v_mfma_f32_16x16x32_bf16 v[116:119], v[176:179], v[192:195], v[116:119]
	v_mfma_f32_16x16x32_bf16 v[112:115], v[184:187], v[192:195], v[112:115]
	v_mfma_f32_16x16x32_bf16 v[100:103], v[176:179], v[200:203], v[100:103]
	v_mfma_f32_16x16x32_bf16 v[96:99], v[184:187], v[200:203], v[96:99]
	v_mfma_f32_16x16x32_bf16 v[84:87], v[176:179], v[212:215], v[84:87]
	v_mfma_f32_16x16x32_bf16 v[80:83], v[184:187], v[212:215], v[80:83]
	v_mfma_f32_16x16x32_bf16 v[68:71], v[176:179], v[220:223], v[68:71]
	v_mfma_f32_16x16x32_bf16 v[64:67], v[184:187], v[220:223], v[64:67]
	s_setprio 0
	s_barrier
	s_add_i32 s94, s76, s48
	s_add_u32 s98, s58, s12
	s_addc_u32 s99, s59, s13
	s_mov_b32 m0, s94
	ds_read_b128 v[188:191], v154 offset:16384
	ds_read_b128 v[192:195], v154 offset:17408
	ds_read_b128 v[196:199], v154 offset:18432
	ds_read_b128 v[200:203], v154 offset:19456
	ds_read_b128 v[204:207], v154 offset:20480
	ds_read_b128 v[212:215], v154 offset:21504
	ds_read_b128 v[216:219], v154 offset:22528
	ds_read_b128 v[220:223], v154 offset:23552
	global_load_lds_dwordx4 v132, s[58:59]
	s_add_i32 m0, s94, 0x2000
	s_add_u32 s94, s58, 0x40000
	s_addc_u32 s95, s59, 0
	s_add_i32 s96, s77, s48
	global_load_lds_dwordx4 v128, s[58:59]
	s_mov_b32 m0, s96
	s_nop 0
	global_load_lds_dwordx4 v132, s[94:95]
	s_add_i32 m0, s96, 0x2000
	s_nop 0
	global_load_lds_dwordx4 v128, s[94:95]
	s_add_u32 s100, s60, s12
	s_addc_u32 s101, s61, s13
	s_mov_b32 m0, s31
	s_nop 0
	global_load_lds_dwordx4 v134, s[60:61]
	s_mov_b32 m0, s68
	s_nop 0
	global_load_lds_dwordx4 v130, s[60:61]
	s_cmp_lg_u32 s33, 0
	s_cbranch_scc1 .Lpg8skip1
	s_waitcnt vmcnt(8)
.Lpg8skip1:
	s_waitcnt lgkmcnt(0)
	s_barrier
	s_setprio 1
	s_waitcnt lgkmcnt(0)
	v_mfma_f32_16x16x32_bf16 v[60:63], v[156:159], v[188:191], v[60:63]
	v_mfma_f32_16x16x32_bf16 v[56:59], v[164:167], v[188:191], v[56:59]
	v_mfma_f32_16x16x32_bf16 v[44:47], v[156:159], v[196:199], v[44:47]
	v_mfma_f32_16x16x32_bf16 v[40:43], v[164:167], v[196:199], v[40:43]
	v_mfma_f32_16x16x32_bf16 v[28:31], v[156:159], v[204:207], v[28:31]
	v_mfma_f32_16x16x32_bf16 v[24:27], v[164:167], v[204:207], v[24:27]
	v_mfma_f32_16x16x32_bf16 v[12:15], v[156:159], v[216:219], v[12:15]
	v_mfma_f32_16x16x32_bf16 v[8:11], v[164:167], v[216:219], v[8:11]
	v_mfma_f32_16x16x32_bf16 v[60:63], v[160:163], v[192:195], v[60:63]
	v_mfma_f32_16x16x32_bf16 v[56:59], v[168:171], v[192:195], v[56:59]
	v_mfma_f32_16x16x32_bf16 v[44:47], v[160:163], v[200:203], v[44:47]
	v_mfma_f32_16x16x32_bf16 v[40:43], v[168:171], v[200:203], v[40:43]
	v_mfma_f32_16x16x32_bf16 v[28:31], v[160:163], v[212:215], v[28:31]
	v_mfma_f32_16x16x32_bf16 v[24:27], v[168:171], v[212:215], v[24:27]
	v_mfma_f32_16x16x32_bf16 v[12:15], v[160:163], v[220:223], v[12:15]
	v_mfma_f32_16x16x32_bf16 v[8:11], v[168:171], v[220:223], v[8:11]
	s_setprio 0
	s_setprio 1
	v_mfma_f32_16x16x32_bf16 v[52:55], v[172:175], v[188:191], v[52:55]
	v_mfma_f32_16x16x32_bf16 v[48:51], v[180:183], v[188:191], v[48:51]
	v_mfma_f32_16x16x32_bf16 v[36:39], v[172:175], v[196:199], v[36:39]
	v_mfma_f32_16x16x32_bf16 v[32:35], v[180:183], v[196:199], v[32:35]
	v_mfma_f32_16x16x32_bf16 v[20:23], v[172:175], v[204:207], v[20:23]
	v_mfma_f32_16x16x32_bf16 v[16:19], v[180:183], v[204:207], v[16:19]
	v_mfma_f32_16x16x32_bf16 v[4:7], v[172:175], v[216:219], v[4:7]
	v_mfma_f32_16x16x32_bf16 v[0:3], v[180:183], v[216:219], v[0:3]
	v_mfma_f32_16x16x32_bf16 v[52:55], v[176:179], v[192:195], v[52:55]
	v_mfma_f32_16x16x32_bf16 v[48:51], v[184:187], v[192:195], v[48:51]
	v_mfma_f32_16x16x32_bf16 v[36:39], v[176:179], v[200:203], v[36:39]
	v_mfma_f32_16x16x32_bf16 v[32:35], v[184:187], v[200:203], v[32:35]
	v_mfma_f32_16x16x32_bf16 v[20:23], v[176:179], v[212:215], v[20:23]
	v_mfma_f32_16x16x32_bf16 v[16:19], v[184:187], v[212:215], v[16:19]
	v_mfma_f32_16x16x32_bf16 v[4:7], v[176:179], v[220:223], v[4:7]
	v_mfma_f32_16x16x32_bf16 v[0:3], v[184:187], v[220:223], v[0:3]
	s_setprio 0
	s_barrier
	s_add_i32 s33, 0, 0x18000
	v_add_u32_e32 v155, s33, v150
	s_add_i32 s94, 0, 0x1c000
	ds_read_b128 v[156:159], v155
	ds_read_b128 v[160:163], v155 offset:1024
	ds_read_b128 v[164:167], v155 offset:2048
	ds_read_b128 v[168:171], v155 offset:3072
	v_add_u32_e32 v155, s94, v150
	ds_read_b128 v[172:175], v155
	ds_read_b128 v[176:179], v155 offset:1024
	ds_read_b128 v[180:183], v155 offset:2048
	ds_read_b128 v[184:187], v155 offset:3072
	s_add_u32 s60, s60, 0x40000
	s_addc_u32 s61, s61, 0
	s_mov_b32 m0, s69
	ds_read_b128 v[188:191], v154 offset:32768
	ds_read_b128 v[192:195], v154 offset:33792
	ds_read_b128 v[196:199], v154 offset:34816
	ds_read_b128 v[200:203], v154 offset:35840
	ds_read_b128 v[204:207], v154 offset:36864
	ds_read_b128 v[212:215], v154 offset:37888
	ds_read_b128 v[216:219], v154 offset:38912
	ds_read_b128 v[220:223], v154 offset:39936
	global_load_lds_dwordx4 v134, s[60:61]
	s_mov_b32 m0, s70
	s_nop 0
	global_load_lds_dwordx4 v130, s[60:61]
	s_waitcnt vmcnt(8)
	s_waitcnt lgkmcnt(0)
	s_barrier
	s_setprio 1
	s_waitcnt lgkmcnt(0)
	v_mfma_f32_16x16x32_bf16 v[124:127], v[156:159], v[188:191], v[124:127]
	v_mfma_f32_16x16x32_bf16 v[120:123], v[164:167], v[188:191], v[120:123]
	v_mfma_f32_16x16x32_bf16 v[108:111], v[156:159], v[196:199], v[108:111]
	v_mfma_f32_16x16x32_bf16 v[104:107], v[164:167], v[196:199], v[104:107]
	v_mfma_f32_16x16x32_bf16 v[92:95], v[156:159], v[204:207], v[92:95]
	v_mfma_f32_16x16x32_bf16 v[88:91], v[164:167], v[204:207], v[88:91]
	v_mfma_f32_16x16x32_bf16 v[76:79], v[156:159], v[216:219], v[76:79]
	v_mfma_f32_16x16x32_bf16 v[72:75], v[164:167], v[216:219], v[72:75]
	v_mfma_f32_16x16x32_bf16 v[124:127], v[160:163], v[192:195], v[124:127]
	v_mfma_f32_16x16x32_bf16 v[120:123], v[168:171], v[192:195], v[120:123]
	v_mfma_f32_16x16x32_bf16 v[108:111], v[160:163], v[200:203], v[108:111]
	v_mfma_f32_16x16x32_bf16 v[104:107], v[168:171], v[200:203], v[104:107]
	v_mfma_f32_16x16x32_bf16 v[92:95], v[160:163], v[212:215], v[92:95]
	v_mfma_f32_16x16x32_bf16 v[88:91], v[168:171], v[212:215], v[88:91]
	v_mfma_f32_16x16x32_bf16 v[76:79], v[160:163], v[220:223], v[76:79]
	v_mfma_f32_16x16x32_bf16 v[72:75], v[168:171], v[220:223], v[72:75]
	s_setprio 0
	s_setprio 1
	v_mfma_f32_16x16x32_bf16 v[116:119], v[172:175], v[188:191], v[116:119]
	v_mfma_f32_16x16x32_bf16 v[112:115], v[180:183], v[188:191], v[112:115]
	v_mfma_f32_16x16x32_bf16 v[100:103], v[172:175], v[196:199], v[100:103]
	v_mfma_f32_16x16x32_bf16 v[96:99], v[180:183], v[196:199], v[96:99]
	v_mfma_f32_16x16x32_bf16 v[84:87], v[172:175], v[204:207], v[84:87]
	v_mfma_f32_16x16x32_bf16 v[80:83], v[180:183], v[204:207], v[80:83]
	v_mfma_f32_16x16x32_bf16 v[68:71], v[172:175], v[216:219], v[68:71]
	v_mfma_f32_16x16x32_bf16 v[64:67], v[180:183], v[216:219], v[64:67]
	v_mfma_f32_16x16x32_bf16 v[116:119], v[176:179], v[192:195], v[116:119]
	v_mfma_f32_16x16x32_bf16 v[112:115], v[184:187], v[192:195], v[112:115]
	v_mfma_f32_16x16x32_bf16 v[100:103], v[176:179], v[200:203], v[100:103]
	v_mfma_f32_16x16x32_bf16 v[96:99], v[184:187], v[200:203], v[96:99]
	v_mfma_f32_16x16x32_bf16 v[84:87], v[176:179], v[212:215], v[84:87]
	v_mfma_f32_16x16x32_bf16 v[80:83], v[184:187], v[212:215], v[80:83]
	v_mfma_f32_16x16x32_bf16 v[68:71], v[176:179], v[220:223], v[68:71]
	v_mfma_f32_16x16x32_bf16 v[64:67], v[184:187], v[220:223], v[64:67]
	s_setprio 0
	s_barrier
	s_add_i32 s33, s33, s48
	s_mov_b32 m0, s33
	ds_read_b128 v[188:191], v154 offset:49152
	ds_read_b128 v[192:195], v154 offset:50176
	ds_read_b128 v[196:199], v154 offset:51200
	ds_read_b128 v[200:203], v154 offset:52224
	ds_read_b128 v[204:207], v154 offset:53248
	ds_read_b128 v[212:215], v154 offset:54272
	ds_read_b128 v[216:219], v154 offset:55296
	ds_read_b128 v[220:223], v154 offset:56320
	global_load_lds_dwordx4 v132, s[98:99]
	s_add_i32 m0, s33, 0x2000
	s_add_u32 s58, s58, 0x40080
	s_addc_u32 s59, s59, 0
	s_add_i32 s33, s94, s48
	global_load_lds_dwordx4 v128, s[98:99]
	s_mov_b32 m0, s33
	s_nop 0
	global_load_lds_dwordx4 v132, s[58:59]
	s_add_i32 m0, s33, 0x2000
	s_nop 0
	global_load_lds_dwordx4 v128, s[58:59]
	s_mov_b32 m0, s71
	s_nop 0
	global_load_lds_dwordx4 v134, s[100:101]
	s_mov_b32 m0, s72
	s_nop 0
	global_load_lds_dwordx4 v130, s[100:101]
	s_waitcnt vmcnt(8)
	s_waitcnt lgkmcnt(0)
	s_barrier
	s_setprio 1
	s_waitcnt lgkmcnt(0)
	v_mfma_f32_16x16x32_bf16 v[60:63], v[156:159], v[188:191], v[60:63]
	v_mfma_f32_16x16x32_bf16 v[56:59], v[164:167], v[188:191], v[56:59]
	v_mfma_f32_16x16x32_bf16 v[44:47], v[156:159], v[196:199], v[44:47]
	v_mfma_f32_16x16x32_bf16 v[40:43], v[164:167], v[196:199], v[40:43]
	v_mfma_f32_16x16x32_bf16 v[28:31], v[156:159], v[204:207], v[28:31]
	v_mfma_f32_16x16x32_bf16 v[24:27], v[164:167], v[204:207], v[24:27]
	v_mfma_f32_16x16x32_bf16 v[12:15], v[156:159], v[216:219], v[12:15]
	v_mfma_f32_16x16x32_bf16 v[8:11], v[164:167], v[216:219], v[8:11]
	v_mfma_f32_16x16x32_bf16 v[60:63], v[160:163], v[192:195], v[60:63]
	v_mfma_f32_16x16x32_bf16 v[56:59], v[168:171], v[192:195], v[56:59]
	v_mfma_f32_16x16x32_bf16 v[44:47], v[160:163], v[200:203], v[44:47]
	v_mfma_f32_16x16x32_bf16 v[40:43], v[168:171], v[200:203], v[40:43]
	v_mfma_f32_16x16x32_bf16 v[28:31], v[160:163], v[212:215], v[28:31]
	v_mfma_f32_16x16x32_bf16 v[24:27], v[168:171], v[212:215], v[24:27]
	v_mfma_f32_16x16x32_bf16 v[12:15], v[160:163], v[220:223], v[12:15]
	v_mfma_f32_16x16x32_bf16 v[8:11], v[168:171], v[220:223], v[8:11]
	s_setprio 0
	s_setprio 1
	v_mfma_f32_16x16x32_bf16 v[52:55], v[172:175], v[188:191], v[52:55]
	v_mfma_f32_16x16x32_bf16 v[48:51], v[180:183], v[188:191], v[48:51]
	v_mfma_f32_16x16x32_bf16 v[36:39], v[172:175], v[196:199], v[36:39]
	v_mfma_f32_16x16x32_bf16 v[32:35], v[180:183], v[196:199], v[32:35]
	v_mfma_f32_16x16x32_bf16 v[20:23], v[172:175], v[204:207], v[20:23]
	v_mfma_f32_16x16x32_bf16 v[16:19], v[180:183], v[204:207], v[16:19]
	v_mfma_f32_16x16x32_bf16 v[4:7], v[172:175], v[216:219], v[4:7]
	v_mfma_f32_16x16x32_bf16 v[0:3], v[180:183], v[216:219], v[0:3]
	v_mfma_f32_16x16x32_bf16 v[52:55], v[176:179], v[192:195], v[52:55]
	v_mfma_f32_16x16x32_bf16 v[48:51], v[184:187], v[192:195], v[48:51]
	v_mfma_f32_16x16x32_bf16 v[36:39], v[176:179], v[200:203], v[36:39]
	v_mfma_f32_16x16x32_bf16 v[32:35], v[184:187], v[200:203], v[32:35]
	v_mfma_f32_16x16x32_bf16 v[20:23], v[176:179], v[212:215], v[20:23]
	v_mfma_f32_16x16x32_bf16 v[16:19], v[184:187], v[212:215], v[16:19]
	v_mfma_f32_16x16x32_bf16 v[4:7], v[176:179], v[220:223], v[4:7]
	v_mfma_f32_16x16x32_bf16 v[0:3], v[184:187], v[220:223], v[0:3]
	s_setprio 0
	s_barrier
	s_add_i32 s93, s93, 2
	s_add_u32 s52, s52, 0x100
	s_addc_u32 s53, s53, 0
	s_cmp_gt_u32 s93, 13
	s_cbranch_scc0 .LBB0_247
	s_and_b64 vcc, exec, s[14:15]
	s_cbranch_vccz .LBB0_250
	s_barrier

.Lpg8skip2:
	s_waitcnt lgkmcnt(0)
	s_barrier
	s_setprio 1
	s_waitcnt lgkmcnt(0)
	v_mfma_f32_16x16x32_bf16 v[124:127], v[144:147], v[182:185], v[124:127]
	v_mfma_f32_16x16x32_bf16 v[120:123], v[158:161], v[182:185], v[120:123]
	v_mfma_f32_16x16x32_bf16 v[112:115], v[144:147], v[190:193], v[112:115]
	v_mfma_f32_16x16x32_bf16 v[108:111], v[158:161], v[190:193], v[108:111]
	v_mfma_f32_16x16x32_bf16 v[96:99], v[144:147], v[198:201], v[96:99]
	v_mfma_f32_16x16x32_bf16 v[92:95], v[158:161], v[198:201], v[92:95]
	v_mfma_f32_16x16x32_bf16 v[80:83], v[144:147], v[212:215], v[80:83]
	v_mfma_f32_16x16x32_bf16 v[76:79], v[158:161], v[212:215], v[76:79]
	v_mfma_f32_16x16x32_bf16 v[124:127], v[148:151], v[186:189], v[124:127]
	v_mfma_f32_16x16x32_bf16 v[120:123], v[162:165], v[186:189], v[120:123]
	v_mfma_f32_16x16x32_bf16 v[112:115], v[148:151], v[194:197], v[112:115]
	v_mfma_f32_16x16x32_bf16 v[108:111], v[162:165], v[194:197], v[108:111]
	v_mfma_f32_16x16x32_bf16 v[96:99], v[148:151], v[202:205], v[96:99]
	v_mfma_f32_16x16x32_bf16 v[92:95], v[162:165], v[202:205], v[92:95]
	v_mfma_f32_16x16x32_bf16 v[80:83], v[148:151], v[216:219], v[80:83]
	v_mfma_f32_16x16x32_bf16 v[76:79], v[162:165], v[216:219], v[76:79]
	s_setprio 0
	s_setprio 1
	v_mfma_f32_16x16x32_bf16 v[116:119], v[166:169], v[182:185], v[116:119]
	v_mfma_f32_16x16x32_bf16 v[104:107], v[174:177], v[182:185], v[104:107]
	v_mfma_f32_16x16x32_bf16 v[100:103], v[166:169], v[190:193], v[100:103]
	v_mfma_f32_16x16x32_bf16 v[88:91], v[174:177], v[190:193], v[88:91]
	v_mfma_f32_16x16x32_bf16 v[84:87], v[166:169], v[198:201], v[84:87]
	v_mfma_f32_16x16x32_bf16 v[72:75], v[174:177], v[198:201], v[72:75]
	v_mfma_f32_16x16x32_bf16 v[68:71], v[166:169], v[212:215], v[68:71]
	v_mfma_f32_16x16x32_bf16 v[64:67], v[174:177], v[212:215], v[64:67]
	v_mfma_f32_16x16x32_bf16 v[116:119], v[170:173], v[186:189], v[116:119]
	v_mfma_f32_16x16x32_bf16 v[104:107], v[178:181], v[186:189], v[104:107]
	v_mfma_f32_16x16x32_bf16 v[100:103], v[170:173], v[194:197], v[100:103]
	v_mfma_f32_16x16x32_bf16 v[88:91], v[178:181], v[194:197], v[88:91]
	v_mfma_f32_16x16x32_bf16 v[84:87], v[170:173], v[202:205], v[84:87]
	v_mfma_f32_16x16x32_bf16 v[72:75], v[178:181], v[202:205], v[72:75]
	v_mfma_f32_16x16x32_bf16 v[68:71], v[170:173], v[216:219], v[68:71]
	v_mfma_f32_16x16x32_bf16 v[64:67], v[178:181], v[216:219], v[64:67]
	s_setprio 0
	s_barrier
	s_add_i32 s26, s70, s36
	s_add_u32 s98, s30, s12
	s_addc_u32 s99, s31, s13
	s_mov_b32 m0, s26
	ds_read_b128 v[182:185], v157 offset:16384
	ds_read_b128 v[186:189], v157 offset:17408
	ds_read_b128 v[190:193], v157 offset:18432
	ds_read_b128 v[194:197], v157 offset:19456
	ds_read_b128 v[198:201], v157 offset:20480
	ds_read_b128 v[202:205], v157 offset:21504
	ds_read_b128 v[212:215], v157 offset:22528
	ds_read_b128 v[216:219], v157 offset:23552
	global_load_lds_dwordx4 v132, s[30:31]
	s_add_i32 m0, s26, 0x2000
	s_add_u32 s26, s30, 0xb0000
	s_addc_u32 s27, s31, 0
	s_add_i32 s33, s71, s36
	global_load_lds_dwordx4 v128, s[30:31]
	s_mov_b32 m0, s33
	s_nop 0
	global_load_lds_dwordx4 v132, s[26:27]
	s_add_i32 m0, s33, 0x2000
	s_nop 0
	global_load_lds_dwordx4 v128, s[26:27]
	s_add_u32 s100, s34, s14
	s_addc_u32 s101, s35, s15
	s_mov_b32 m0, s37
	s_nop 0
	global_load_lds_dwordx4 v134, s[34:35]
	s_mov_b32 m0, s48
	s_nop 0
	global_load_lds_dwordx4 v130, s[34:35]
	s_cmp_lg_u32 s53, 0
	s_cbranch_scc1 .Lpg8skip3
	s_waitcnt vmcnt(8)
.Lpg8skip3:
	s_waitcnt lgkmcnt(0)
	s_barrier
	s_setprio 1
	s_waitcnt lgkmcnt(0)
	v_mfma_f32_16x16x32_bf16 v[60:63], v[144:147], v[182:185], v[60:63]
	v_mfma_f32_16x16x32_bf16 v[56:59], v[158:161], v[182:185], v[56:59]
	v_mfma_f32_16x16x32_bf16 v[48:51], v[144:147], v[190:193], v[48:51]
	v_mfma_f32_16x16x32_bf16 v[44:47], v[158:161], v[190:193], v[44:47]
	v_mfma_f32_16x16x32_bf16 v[32:35], v[144:147], v[198:201], v[32:35]
	v_mfma_f32_16x16x32_bf16 v[28:31], v[158:161], v[198:201], v[28:31]
	v_mfma_f32_16x16x32_bf16 v[16:19], v[144:147], v[212:215], v[16:19]
	v_mfma_f32_16x16x32_bf16 v[12:15], v[158:161], v[212:215], v[12:15]
	v_mfma_f32_16x16x32_bf16 v[60:63], v[148:151], v[186:189], v[60:63]
	v_mfma_f32_16x16x32_bf16 v[56:59], v[162:165], v[186:189], v[56:59]
	v_mfma_f32_16x16x32_bf16 v[48:51], v[148:151], v[194:197], v[48:51]
	v_mfma_f32_16x16x32_bf16 v[44:47], v[162:165], v[194:197], v[44:47]
	v_mfma_f32_16x16x32_bf16 v[32:35], v[148:151], v[202:205], v[32:35]
	v_mfma_f32_16x16x32_bf16 v[28:31], v[162:165], v[202:205], v[28:31]
	v_mfma_f32_16x16x32_bf16 v[16:19], v[148:151], v[216:219], v[16:19]
	v_mfma_f32_16x16x32_bf16 v[12:15], v[162:165], v[216:219], v[12:15]
	s_setprio 0
	s_setprio 1
	v_mfma_f32_16x16x32_bf16 v[52:55], v[166:169], v[182:185], v[52:55]
	v_mfma_f32_16x16x32_bf16 v[40:43], v[174:177], v[182:185], v[40:43]
	v_mfma_f32_16x16x32_bf16 v[36:39], v[166:169], v[190:193], v[36:39]
	v_mfma_f32_16x16x32_bf16 v[24:27], v[174:177], v[190:193], v[24:27]
	v_mfma_f32_16x16x32_bf16 v[20:23], v[166:169], v[198:201], v[20:23]
	v_mfma_f32_16x16x32_bf16 v[8:11], v[174:177], v[198:201], v[8:11]
	v_mfma_f32_16x16x32_bf16 v[4:7], v[166:169], v[212:215], v[4:7]
	v_mfma_f32_16x16x32_bf16 v[0:3], v[174:177], v[212:215], v[0:3]
	v_mfma_f32_16x16x32_bf16 v[52:55], v[170:173], v[186:189], v[52:55]
	v_mfma_f32_16x16x32_bf16 v[40:43], v[178:181], v[186:189], v[40:43]
	v_mfma_f32_16x16x32_bf16 v[36:39], v[170:173], v[194:197], v[36:39]
	v_mfma_f32_16x16x32_bf16 v[24:27], v[178:181], v[194:197], v[24:27]
	v_mfma_f32_16x16x32_bf16 v[20:23], v[170:173], v[202:205], v[20:23]
	v_mfma_f32_16x16x32_bf16 v[8:11], v[178:181], v[202:205], v[8:11]
	v_mfma_f32_16x16x32_bf16 v[4:7], v[170:173], v[216:219], v[4:7]
	v_mfma_f32_16x16x32_bf16 v[0:3], v[178:181], v[216:219], v[0:3]
	s_setprio 0
	s_barrier
	s_add_i32 s33, 0, 0x18000
	s_add_i32 s81, 0, 0x1c000
	v_add_u32_e32 v162, s33, v153
	v_add_u32_e32 v178, s81, v153
	ds_read_b128 v[144:147], v162
	ds_read_b128 v[148:151], v162 offset:1024
	ds_read_b128 v[158:161], v162 offset:2048
	ds_read_b128 v[162:165], v162 offset:3072
	ds_read_b128 v[166:169], v178
	ds_read_b128 v[170:173], v178 offset:1024
	ds_read_b128 v[174:177], v178 offset:2048
	ds_read_b128 v[178:181], v178 offset:3072
	s_add_u32 s26, s34, 0xb0000
	s_addc_u32 s27, s35, 0
	s_mov_b32 m0, s49
	ds_read_b128 v[182:185], v157 offset:32768
	ds_read_b128 v[186:189], v157 offset:33792
	ds_read_b128 v[190:193], v157 offset:34816
	ds_read_b128 v[194:197], v157 offset:35840
	ds_read_b128 v[198:201], v157 offset:36864
	ds_read_b128 v[202:205], v157 offset:37888
	ds_read_b128 v[212:215], v157 offset:38912
	ds_read_b128 v[216:219], v157 offset:39936
	global_load_lds_dwordx4 v134, s[26:27]
	s_mov_b32 m0, s52
	s_nop 0
	global_load_lds_dwordx4 v130, s[26:27]
	s_waitcnt vmcnt(8)
	s_waitcnt lgkmcnt(0)
	s_barrier
	s_setprio 1
	s_waitcnt lgkmcnt(0)
	v_mfma_f32_16x16x32_bf16 v[124:127], v[144:147], v[182:185], v[124:127]
	v_mfma_f32_16x16x32_bf16 v[120:123], v[158:161], v[182:185], v[120:123]
	v_mfma_f32_16x16x32_bf16 v[112:115], v[144:147], v[190:193], v[112:115]
	v_mfma_f32_16x16x32_bf16 v[108:111], v[158:161], v[190:193], v[108:111]
	v_mfma_f32_16x16x32_bf16 v[96:99], v[144:147], v[198:201], v[96:99]
	v_mfma_f32_16x16x32_bf16 v[92:95], v[158:161], v[198:201], v[92:95]
	v_mfma_f32_16x16x32_bf16 v[80:83], v[144:147], v[212:215], v[80:83]
	v_mfma_f32_16x16x32_bf16 v[76:79], v[158:161], v[212:215], v[76:79]
	v_mfma_f32_16x16x32_bf16 v[124:127], v[148:151], v[186:189], v[124:127]
	v_mfma_f32_16x16x32_bf16 v[120:123], v[162:165], v[186:189], v[120:123]
	v_mfma_f32_16x16x32_bf16 v[112:115], v[148:151], v[194:197], v[112:115]
	v_mfma_f32_16x16x32_bf16 v[108:111], v[162:165], v[194:197], v[108:111]
	v_mfma_f32_16x16x32_bf16 v[96:99], v[148:151], v[202:205], v[96:99]
	v_mfma_f32_16x16x32_bf16 v[92:95], v[162:165], v[202:205], v[92:95]
	v_mfma_f32_16x16x32_bf16 v[80:83], v[148:151], v[216:219], v[80:83]
	v_mfma_f32_16x16x32_bf16 v[76:79], v[162:165], v[216:219], v[76:79]
	s_setprio 0
	s_setprio 1
	v_mfma_f32_16x16x32_bf16 v[116:119], v[166:169], v[182:185], v[116:119]
	v_mfma_f32_16x16x32_bf16 v[104:107], v[174:177], v[182:185], v[104:107]
	v_mfma_f32_16x16x32_bf16 v[100:103], v[166:169], v[190:193], v[100:103]
	v_mfma_f32_16x16x32_bf16 v[88:91], v[174:177], v[190:193], v[88:91]
	v_mfma_f32_16x16x32_bf16 v[84:87], v[166:169], v[198:201], v[84:87]
	v_mfma_f32_16x16x32_bf16 v[72:75], v[174:177], v[198:201], v[72:75]
	v_mfma_f32_16x16x32_bf16 v[68:71], v[166:169], v[212:215], v[68:71]
	v_mfma_f32_16x16x32_bf16 v[64:67], v[174:177], v[212:215], v[64:67]
	v_mfma_f32_16x16x32_bf16 v[116:119], v[170:173], v[186:189], v[116:119]
	v_mfma_f32_16x16x32_bf16 v[104:107], v[178:181], v[186:189], v[104:107]
	v_mfma_f32_16x16x32_bf16 v[100:103], v[170:173], v[194:197], v[100:103]
	v_mfma_f32_16x16x32_bf16 v[88:91], v[178:181], v[194:197], v[88:91]
	v_mfma_f32_16x16x32_bf16 v[84:87], v[170:173], v[202:205], v[84:87]
	v_mfma_f32_16x16x32_bf16 v[72:75], v[178:181], v[202:205], v[72:75]
	v_mfma_f32_16x16x32_bf16 v[68:71], v[170:173], v[216:219], v[68:71]
	v_mfma_f32_16x16x32_bf16 v[64:67], v[178:181], v[216:219], v[64:67]
	s_setprio 0
	s_barrier
	s_add_i32 s26, s33, s36
	s_mov_b32 m0, s26
	ds_read_b128 v[182:185], v157 offset:49152
	ds_read_b128 v[186:189], v157 offset:50176
	ds_read_b128 v[190:193], v157 offset:51200
	ds_read_b128 v[194:197], v157 offset:52224
	ds_read_b128 v[198:201], v157 offset:53248
	ds_read_b128 v[202:205], v157 offset:54272
	ds_read_b128 v[212:215], v157 offset:55296
	ds_read_b128 v[216:219], v157 offset:56320
	global_load_lds_dwordx4 v132, s[98:99]
	s_add_i32 m0, s26, 0x2000
	s_add_u32 s26, s30, 0xb0080
	s_addc_u32 s27, s31, 0
	s_add_i32 s30, s81, s36
	global_load_lds_dwordx4 v128, s[98:99]
	s_mov_b32 m0, s30
	s_nop 0
	global_load_lds_dwordx4 v132, s[26:27]
	s_add_i32 m0, s30, 0x2000
	s_nop 0
	global_load_lds_dwordx4 v128, s[26:27]
	s_mov_b32 m0, s60
	s_nop 0
	global_load_lds_dwordx4 v134, s[100:101]
	s_mov_b32 m0, s61
	s_nop 0
	global_load_lds_dwordx4 v130, s[100:101]
	s_waitcnt vmcnt(8)
	s_waitcnt lgkmcnt(0)
	s_barrier
	s_setprio 1
	s_waitcnt lgkmcnt(0)
	v_mfma_f32_16x16x32_bf16 v[60:63], v[144:147], v[182:185], v[60:63]
	v_mfma_f32_16x16x32_bf16 v[56:59], v[158:161], v[182:185], v[56:59]
	v_mfma_f32_16x16x32_bf16 v[48:51], v[144:147], v[190:193], v[48:51]
	v_mfma_f32_16x16x32_bf16 v[44:47], v[158:161], v[190:193], v[44:47]
	v_mfma_f32_16x16x32_bf16 v[32:35], v[144:147], v[198:201], v[32:35]
	v_mfma_f32_16x16x32_bf16 v[28:31], v[158:161], v[198:201], v[28:31]
	v_mfma_f32_16x16x32_bf16 v[16:19], v[144:147], v[212:215], v[16:19]
	v_mfma_f32_16x16x32_bf16 v[12:15], v[158:161], v[212:215], v[12:15]
	v_mfma_f32_16x16x32_bf16 v[60:63], v[148:151], v[186:189], v[60:63]
	v_mfma_f32_16x16x32_bf16 v[56:59], v[162:165], v[186:189], v[56:59]
	v_mfma_f32_16x16x32_bf16 v[48:51], v[148:151], v[194:197], v[48:51]
	v_mfma_f32_16x16x32_bf16 v[44:47], v[162:165], v[194:197], v[44:47]
	v_mfma_f32_16x16x32_bf16 v[32:35], v[148:151], v[202:205], v[32:35]
	v_mfma_f32_16x16x32_bf16 v[28:31], v[162:165], v[202:205], v[28:31]
	v_mfma_f32_16x16x32_bf16 v[16:19], v[148:151], v[216:219], v[16:19]
	v_mfma_f32_16x16x32_bf16 v[12:15], v[162:165], v[216:219], v[12:15]
	s_setprio 0
	s_setprio 1
	v_mfma_f32_16x16x32_bf16 v[52:55], v[166:169], v[182:185], v[52:55]
	v_mfma_f32_16x16x32_bf16 v[40:43], v[174:177], v[182:185], v[40:43]
	v_mfma_f32_16x16x32_bf16 v[36:39], v[166:169], v[190:193], v[36:39]
	v_mfma_f32_16x16x32_bf16 v[24:27], v[174:177], v[190:193], v[24:27]
	v_mfma_f32_16x16x32_bf16 v[20:23], v[166:169], v[198:201], v[20:23]
	v_mfma_f32_16x16x32_bf16 v[8:11], v[174:177], v[198:201], v[8:11]
	v_mfma_f32_16x16x32_bf16 v[4:7], v[166:169], v[212:215], v[4:7]
	v_mfma_f32_16x16x32_bf16 v[0:3], v[174:177], v[212:215], v[0:3]
	v_mfma_f32_16x16x32_bf16 v[52:55], v[170:173], v[186:189], v[52:55]
	v_mfma_f32_16x16x32_bf16 v[40:43], v[178:181], v[186:189], v[40:43]
	v_mfma_f32_16x16x32_bf16 v[36:39], v[170:173], v[194:197], v[36:39]
	v_mfma_f32_16x16x32_bf16 v[24:27], v[178:181], v[194:197], v[24:27]
	v_mfma_f32_16x16x32_bf16 v[20:23], v[170:173], v[202:205], v[20:23]
	v_mfma_f32_16x16x32_bf16 v[8:11], v[178:181], v[202:205], v[8:11]
	v_mfma_f32_16x16x32_bf16 v[4:7], v[170:173], v[216:219], v[4:7]
	v_mfma_f32_16x16x32_bf16 v[0:3], v[178:181], v[216:219], v[0:3]
	s_setprio 0
	s_barrier
	s_add_i32 s80, s80, 2
	s_add_u32 s78, s78, 0x100
	s_addc_u32 s79, s79, 0
	s_cmp_gt_u32 s80, 41
	s_mov_b64 s[26:27], s[28:29]
	s_cbranch_scc0 .LBB0_324
	s_and_b64 vcc, exec, s[16:17]
	s_cbranch_vccz .LBB0_327
	s_barrier

.LBB0_491:
	ds_read_b128 v[128:131], v178
	ds_read_b128 v[132:135], v178 offset:1024
	ds_read_b128 v[158:161], v178 offset:2048
	ds_read_b128 v[162:165], v178 offset:3072
	ds_read_b128 v[166:169], v179
	ds_read_b128 v[170:173], v179 offset:1024
	ds_read_b128 v[174:177], v179 offset:2048
	ds_read_b128 v[186:189], v179 offset:3072
	s_add_u32 s28, s26, 0xfffc0080
	s_addc_u32 s29, s27, -1
	s_cmp_eq_u32 s68, 12
	s_cselect_b32 s31, s1, s29
	s_cselect_b32 s30, s7, s28
	s_cselect_b32 s29, s8, s21
	s_cselect_b32 s28, s17, s19
	s_add_i32 m0, s37, 0xc000
	ds_read_b128 v[190:193], v180
	ds_read_b128 v[194:197], v180 offset:1024
	ds_read_b128 v[198:201], v180 offset:2048
	ds_read_b128 v[202:205], v180 offset:3072
	ds_read_b128 v[212:215], v180 offset:4096
	ds_read_b128 v[216:219], v180 offset:5120
	ds_read_b128 v[220:223], v180 offset:6144
	ds_read_b128 v[224:227], v180 offset:7168
	global_load_lds_dwordx4 v150, s[26:27]
	s_add_i32 m0, s37, 0xe000
	s_nop 0
	global_load_lds_dwordx4 v152, s[26:27]
	s_cmp_lg_u32 s9, 0
	s_cbranch_scc1 .Lpg8skip4
	s_waitcnt vmcnt(8)
.Lpg8skip4:
	s_waitcnt lgkmcnt(0)
	s_barrier
	s_setprio 1
	s_waitcnt lgkmcnt(0)
	v_mfma_f32_16x16x32_bf16 v[124:127], v[128:131], v[190:193], v[124:127]
	v_mfma_f32_16x16x32_bf16 v[120:123], v[158:161], v[190:193], v[120:123]
	v_mfma_f32_16x16x32_bf16 v[108:111], v[128:131], v[198:201], v[108:111]
	v_mfma_f32_16x16x32_bf16 v[104:107], v[158:161], v[198:201], v[104:107]
	v_mfma_f32_16x16x32_bf16 v[92:95], v[128:131], v[212:215], v[92:95]
	v_mfma_f32_16x16x32_bf16 v[88:91], v[158:161], v[212:215], v[88:91]
	v_mfma_f32_16x16x32_bf16 v[76:79], v[128:131], v[220:223], v[76:79]
	v_mfma_f32_16x16x32_bf16 v[72:75], v[158:161], v[220:223], v[72:75]
	v_mfma_f32_16x16x32_bf16 v[124:127], v[132:135], v[194:197], v[124:127]
	v_mfma_f32_16x16x32_bf16 v[120:123], v[162:165], v[194:197], v[120:123]
	v_mfma_f32_16x16x32_bf16 v[108:111], v[132:135], v[202:205], v[108:111]
	v_mfma_f32_16x16x32_bf16 v[104:107], v[162:165], v[202:205], v[104:107]
	v_mfma_f32_16x16x32_bf16 v[92:95], v[132:135], v[216:219], v[92:95]
	v_mfma_f32_16x16x32_bf16 v[88:91], v[162:165], v[216:219], v[88:91]
	v_mfma_f32_16x16x32_bf16 v[76:79], v[132:135], v[224:227], v[76:79]
	v_mfma_f32_16x16x32_bf16 v[72:75], v[162:165], v[224:227], v[72:75]
	s_setprio 0
	s_setprio 1
	v_mfma_f32_16x16x32_bf16 v[116:119], v[166:169], v[190:193], v[116:119]
	v_mfma_f32_16x16x32_bf16 v[112:115], v[174:177], v[190:193], v[112:115]
	v_mfma_f32_16x16x32_bf16 v[100:103], v[166:169], v[198:201], v[100:103]
	v_mfma_f32_16x16x32_bf16 v[96:99], v[174:177], v[198:201], v[96:99]
	v_mfma_f32_16x16x32_bf16 v[84:87], v[166:169], v[212:215], v[84:87]
	v_mfma_f32_16x16x32_bf16 v[80:83], v[174:177], v[212:215], v[80:83]
	v_mfma_f32_16x16x32_bf16 v[68:71], v[166:169], v[220:223], v[68:71]
	v_mfma_f32_16x16x32_bf16 v[64:67], v[174:177], v[220:223], v[64:67]
	v_mfma_f32_16x16x32_bf16 v[116:119], v[170:173], v[194:197], v[116:119]
	v_mfma_f32_16x16x32_bf16 v[112:115], v[186:189], v[194:197], v[112:115]
	v_mfma_f32_16x16x32_bf16 v[100:103], v[170:173], v[202:205], v[100:103]
	v_mfma_f32_16x16x32_bf16 v[96:99], v[186:189], v[202:205], v[96:99]
	v_mfma_f32_16x16x32_bf16 v[84:87], v[170:173], v[216:219], v[84:87]
	v_mfma_f32_16x16x32_bf16 v[80:83], v[186:189], v[216:219], v[80:83]
	v_mfma_f32_16x16x32_bf16 v[68:71], v[170:173], v[224:227], v[68:71]
	v_mfma_f32_16x16x32_bf16 v[64:67], v[186:189], v[224:227], v[64:67]
	s_setprio 0
	s_barrier
	s_add_i32 s33, s72, s36
	s_add_u32 s98, s28, s12
	s_addc_u32 s99, s29, s13
	s_mov_b32 m0, s33
	ds_read_b128 v[190:193], v180 offset:16384
	ds_read_b128 v[194:197], v180 offset:17408
	ds_read_b128 v[198:201], v180 offset:18432
	ds_read_b128 v[202:205], v180 offset:19456
	ds_read_b128 v[212:215], v180 offset:20480
	ds_read_b128 v[216:219], v180 offset:21504
	ds_read_b128 v[220:223], v180 offset:22528
	ds_read_b128 v[224:227], v180 offset:23552
	global_load_lds_dwordx4 v138, s[28:29]
	s_add_i32 m0, s33, 0x2000
	s_add_u32 s82, s28, 0x40000
	s_addc_u32 s83, s29, 0
	s_add_i32 s33, s73, s36
	global_load_lds_dwordx4 v142, s[28:29]
	s_mov_b32 m0, s33
	s_nop 0
	global_load_lds_dwordx4 v138, s[82:83]
	s_add_i32 m0, s33, 0x2000
	s_nop 0
	global_load_lds_dwordx4 v142, s[82:83]
	s_add_u32 s100, s30, s12
	s_addc_u32 s101, s31, s13
	s_mov_b32 m0, s37
	s_nop 0
	global_load_lds_dwordx4 v136, s[30:31]
	s_mov_b32 m0, s42
	s_nop 0
	global_load_lds_dwordx4 v140, s[30:31]
	s_cmp_lg_u32 s9, 0
	s_cbranch_scc1 .Lpg8skip5
	s_waitcnt vmcnt(8)
.Lpg8skip5:
	s_waitcnt lgkmcnt(0)
	s_barrier
	s_setprio 1
	s_waitcnt lgkmcnt(0)
	v_mfma_f32_16x16x32_bf16 v[60:63], v[128:131], v[190:193], v[60:63]
	v_mfma_f32_16x16x32_bf16 v[56:59], v[158:161], v[190:193], v[56:59]
	v_mfma_f32_16x16x32_bf16 v[44:47], v[128:131], v[198:201], v[44:47]
	v_mfma_f32_16x16x32_bf16 v[40:43], v[158:161], v[198:201], v[40:43]
	v_mfma_f32_16x16x32_bf16 v[28:31], v[128:131], v[212:215], v[28:31]
	v_mfma_f32_16x16x32_bf16 v[24:27], v[158:161], v[212:215], v[24:27]
	v_mfma_f32_16x16x32_bf16 v[12:15], v[128:131], v[220:223], v[12:15]
	v_mfma_f32_16x16x32_bf16 v[8:11], v[158:161], v[220:223], v[8:11]
	v_mfma_f32_16x16x32_bf16 v[60:63], v[132:135], v[194:197], v[60:63]
	v_mfma_f32_16x16x32_bf16 v[56:59], v[162:165], v[194:197], v[56:59]
	v_mfma_f32_16x16x32_bf16 v[44:47], v[132:135], v[202:205], v[44:47]
	v_mfma_f32_16x16x32_bf16 v[40:43], v[162:165], v[202:205], v[40:43]
	v_mfma_f32_16x16x32_bf16 v[28:31], v[132:135], v[216:219], v[28:31]
	v_mfma_f32_16x16x32_bf16 v[24:27], v[162:165], v[216:219], v[24:27]
	v_mfma_f32_16x16x32_bf16 v[12:15], v[132:135], v[224:227], v[12:15]
	v_mfma_f32_16x16x32_bf16 v[8:11], v[162:165], v[224:227], v[8:11]
	s_setprio 0
	s_setprio 1
	v_mfma_f32_16x16x32_bf16 v[52:55], v[166:169], v[190:193], v[52:55]
	v_mfma_f32_16x16x32_bf16 v[48:51], v[174:177], v[190:193], v[48:51]
	v_mfma_f32_16x16x32_bf16 v[36:39], v[166:169], v[198:201], v[36:39]
	v_mfma_f32_16x16x32_bf16 v[32:35], v[174:177], v[198:201], v[32:35]
	v_mfma_f32_16x16x32_bf16 v[20:23], v[166:169], v[212:215], v[20:23]
	v_mfma_f32_16x16x32_bf16 v[16:19], v[174:177], v[212:215], v[16:19]
	v_mfma_f32_16x16x32_bf16 v[4:7], v[166:169], v[220:223], v[4:7]
	v_mfma_f32_16x16x32_bf16 v[0:3], v[174:177], v[220:223], v[0:3]
	v_mfma_f32_16x16x32_bf16 v[52:55], v[170:173], v[194:197], v[52:55]
	v_mfma_f32_16x16x32_bf16 v[48:51], v[186:189], v[194:197], v[48:51]
	v_mfma_f32_16x16x32_bf16 v[36:39], v[170:173], v[202:205], v[36:39]
	v_mfma_f32_16x16x32_bf16 v[32:35], v[186:189], v[202:205], v[32:35]
	v_mfma_f32_16x16x32_bf16 v[20:23], v[170:173], v[216:219], v[20:23]
	v_mfma_f32_16x16x32_bf16 v[16:19], v[186:189], v[216:219], v[16:19]
	v_mfma_f32_16x16x32_bf16 v[4:7], v[170:173], v[224:227], v[4:7]
	v_mfma_f32_16x16x32_bf16 v[0:3], v[186:189], v[224:227], v[0:3]
	s_setprio 0
	s_barrier
	s_add_i32 s33, 0, 0x18000
	v_add_u32_e32 v144, s33, v149
	s_add_i32 s69, 0, 0x1c000
	ds_read_b128 v[128:131], v144
	ds_read_b128 v[132:135], v144 offset:1024
	ds_read_b128 v[158:161], v144 offset:2048
	ds_read_b128 v[162:165], v144 offset:3072
	v_add_u32_e32 v144, s69, v149
	ds_read_b128 v[166:169], v144
	ds_read_b128 v[170:173], v144 offset:1024
	ds_read_b128 v[174:177], v144 offset:2048
	ds_read_b128 v[186:189], v144 offset:3072
	s_add_u32 s30, s30, 0x40000
	s_addc_u32 s31, s31, 0
	s_mov_b32 m0, s43
	ds_read_b128 v[190:193], v180 offset:32768
	ds_read_b128 v[194:197], v180 offset:33792
	ds_read_b128 v[198:201], v180 offset:34816
	ds_read_b128 v[202:205], v180 offset:35840
	ds_read_b128 v[212:215], v180 offset:36864
	ds_read_b128 v[216:219], v180 offset:37888
	ds_read_b128 v[220:223], v180 offset:38912
	ds_read_b128 v[224:227], v180 offset:39936
	global_load_lds_dwordx4 v136, s[30:31]
	s_mov_b32 m0, s48
	s_nop 0
	global_load_lds_dwordx4 v140, s[30:31]
	s_waitcnt vmcnt(8)
	s_waitcnt lgkmcnt(0)
	s_barrier
	s_setprio 1
	s_waitcnt lgkmcnt(0)
	v_mfma_f32_16x16x32_bf16 v[124:127], v[128:131], v[190:193], v[124:127]
	v_mfma_f32_16x16x32_bf16 v[120:123], v[158:161], v[190:193], v[120:123]
	v_mfma_f32_16x16x32_bf16 v[108:111], v[128:131], v[198:201], v[108:111]
	v_mfma_f32_16x16x32_bf16 v[104:107], v[158:161], v[198:201], v[104:107]
	v_mfma_f32_16x16x32_bf16 v[92:95], v[128:131], v[212:215], v[92:95]
	v_mfma_f32_16x16x32_bf16 v[88:91], v[158:161], v[212:215], v[88:91]
	v_mfma_f32_16x16x32_bf16 v[76:79], v[128:131], v[220:223], v[76:79]
	v_mfma_f32_16x16x32_bf16 v[72:75], v[158:161], v[220:223], v[72:75]
	v_mfma_f32_16x16x32_bf16 v[124:127], v[132:135], v[194:197], v[124:127]
	v_mfma_f32_16x16x32_bf16 v[120:123], v[162:165], v[194:197], v[120:123]
	v_mfma_f32_16x16x32_bf16 v[108:111], v[132:135], v[202:205], v[108:111]
	v_mfma_f32_16x16x32_bf16 v[104:107], v[162:165], v[202:205], v[104:107]
	v_mfma_f32_16x16x32_bf16 v[92:95], v[132:135], v[216:219], v[92:95]
	v_mfma_f32_16x16x32_bf16 v[88:91], v[162:165], v[216:219], v[88:91]
	v_mfma_f32_16x16x32_bf16 v[76:79], v[132:135], v[224:227], v[76:79]
	v_mfma_f32_16x16x32_bf16 v[72:75], v[162:165], v[224:227], v[72:75]
	s_setprio 0
	s_setprio 1
	v_mfma_f32_16x16x32_bf16 v[116:119], v[166:169], v[190:193], v[116:119]
	v_mfma_f32_16x16x32_bf16 v[112:115], v[174:177], v[190:193], v[112:115]
	v_mfma_f32_16x16x32_bf16 v[100:103], v[166:169], v[198:201], v[100:103]
	v_mfma_f32_16x16x32_bf16 v[96:99], v[174:177], v[198:201], v[96:99]
	v_mfma_f32_16x16x32_bf16 v[84:87], v[166:169], v[212:215], v[84:87]
	v_mfma_f32_16x16x32_bf16 v[80:83], v[174:177], v[212:215], v[80:83]
	v_mfma_f32_16x16x32_bf16 v[68:71], v[166:169], v[220:223], v[68:71]
	v_mfma_f32_16x16x32_bf16 v[64:67], v[174:177], v[220:223], v[64:67]
	v_mfma_f32_16x16x32_bf16 v[116:119], v[170:173], v[194:197], v[116:119]
	v_mfma_f32_16x16x32_bf16 v[112:115], v[186:189], v[194:197], v[112:115]
	v_mfma_f32_16x16x32_bf16 v[100:103], v[170:173], v[202:205], v[100:103]
	v_mfma_f32_16x16x32_bf16 v[96:99], v[186:189], v[202:205], v[96:99]
	v_mfma_f32_16x16x32_bf16 v[84:87], v[170:173], v[216:219], v[84:87]
	v_mfma_f32_16x16x32_bf16 v[80:83], v[186:189], v[216:219], v[80:83]
	v_mfma_f32_16x16x32_bf16 v[68:71], v[170:173], v[224:227], v[68:71]
	v_mfma_f32_16x16x32_bf16 v[64:67], v[186:189], v[224:227], v[64:67]
	s_setprio 0
	s_barrier
	s_add_i32 s30, s33, s36
	s_mov_b32 m0, s30
	ds_read_b128 v[190:193], v180 offset:49152
	ds_read_b128 v[194:197], v180 offset:50176
	ds_read_b128 v[198:201], v180 offset:51200
	ds_read_b128 v[202:205], v180 offset:52224
	ds_read_b128 v[212:215], v180 offset:53248
	ds_read_b128 v[216:219], v180 offset:54272
	ds_read_b128 v[220:223], v180 offset:55296
	ds_read_b128 v[224:227], v180 offset:56320
	global_load_lds_dwordx4 v138, s[98:99]
	s_add_i32 m0, s30, 0x2000
	s_add_u32 s28, s28, 0x40080
	s_addc_u32 s29, s29, 0
	s_add_i32 s30, s69, s36
	global_load_lds_dwordx4 v142, s[98:99]
	s_mov_b32 m0, s30
	s_nop 0
	global_load_lds_dwordx4 v138, s[28:29]
	s_add_i32 m0, s30, 0x2000
	s_nop 0
	global_load_lds_dwordx4 v142, s[28:29]
	s_mov_b32 m0, s52
	s_nop 0
	global_load_lds_dwordx4 v136, s[100:101]
	s_mov_b32 m0, s53
	s_nop 0
	global_load_lds_dwordx4 v140, s[100:101]
	s_waitcnt vmcnt(8)
	s_waitcnt lgkmcnt(0)
	s_barrier
	s_setprio 1
	s_waitcnt lgkmcnt(0)
	v_mfma_f32_16x16x32_bf16 v[60:63], v[128:131], v[190:193], v[60:63]
	v_mfma_f32_16x16x32_bf16 v[56:59], v[158:161], v[190:193], v[56:59]
	v_mfma_f32_16x16x32_bf16 v[44:47], v[128:131], v[198:201], v[44:47]
	v_mfma_f32_16x16x32_bf16 v[40:43], v[158:161], v[198:201], v[40:43]
	v_mfma_f32_16x16x32_bf16 v[28:31], v[128:131], v[212:215], v[28:31]
	v_mfma_f32_16x16x32_bf16 v[24:27], v[158:161], v[212:215], v[24:27]
	v_mfma_f32_16x16x32_bf16 v[12:15], v[128:131], v[220:223], v[12:15]
	v_mfma_f32_16x16x32_bf16 v[8:11], v[158:161], v[220:223], v[8:11]
	v_mfma_f32_16x16x32_bf16 v[60:63], v[132:135], v[194:197], v[60:63]
	v_mfma_f32_16x16x32_bf16 v[56:59], v[162:165], v[194:197], v[56:59]
	v_mfma_f32_16x16x32_bf16 v[44:47], v[132:135], v[202:205], v[44:47]
	v_mfma_f32_16x16x32_bf16 v[40:43], v[162:165], v[202:205], v[40:43]
	v_mfma_f32_16x16x32_bf16 v[28:31], v[132:135], v[216:219], v[28:31]
	v_mfma_f32_16x16x32_bf16 v[24:27], v[162:165], v[216:219], v[24:27]
	v_mfma_f32_16x16x32_bf16 v[12:15], v[132:135], v[224:227], v[12:15]
	v_mfma_f32_16x16x32_bf16 v[8:11], v[162:165], v[224:227], v[8:11]
	s_setprio 0
	s_setprio 1
	v_mfma_f32_16x16x32_bf16 v[52:55], v[166:169], v[190:193], v[52:55]
	v_mfma_f32_16x16x32_bf16 v[48:51], v[174:177], v[190:193], v[48:51]
	v_mfma_f32_16x16x32_bf16 v[36:39], v[166:169], v[198:201], v[36:39]
	v_mfma_f32_16x16x32_bf16 v[32:35], v[174:177], v[198:201], v[32:35]
	v_mfma_f32_16x16x32_bf16 v[20:23], v[166:169], v[212:215], v[20:23]
	v_mfma_f32_16x16x32_bf16 v[16:19], v[174:177], v[212:215], v[16:19]
	v_mfma_f32_16x16x32_bf16 v[4:7], v[166:169], v[220:223], v[4:7]
	v_mfma_f32_16x16x32_bf16 v[0:3], v[174:177], v[220:223], v[0:3]
	v_mfma_f32_16x16x32_bf16 v[52:55], v[170:173], v[194:197], v[52:55]
	v_mfma_f32_16x16x32_bf16 v[48:51], v[186:189], v[194:197], v[48:51]
	v_mfma_f32_16x16x32_bf16 v[36:39], v[170:173], v[202:205], v[36:39]
	v_mfma_f32_16x16x32_bf16 v[32:35], v[186:189], v[202:205], v[32:35]
	v_mfma_f32_16x16x32_bf16 v[20:23], v[170:173], v[216:219], v[20:23]
	v_mfma_f32_16x16x32_bf16 v[16:19], v[186:189], v[216:219], v[16:19]
	v_mfma_f32_16x16x32_bf16 v[4:7], v[170:173], v[224:227], v[4:7]
	v_mfma_f32_16x16x32_bf16 v[0:3], v[186:189], v[224:227], v[0:3]
	s_setprio 0
	s_barrier
	s_add_i32 s68, s68, 2
	s_add_u32 s26, s26, 0x100
	s_addc_u32 s27, s27, 0
	s_add_u32 s19, s19, 0x100
	s_addc_u32 s21, s21, 0
	s_cmp_gt_u32 s68, 13
	s_cbranch_scc0 .LBB0_491
	s_and_b64 vcc, exec, s[14:15]
	s_cbranch_vccz .LBB0_494
	s_barrier

.LBB0_811:
	s_waitcnt lgkmcnt(0)
	s_barrier
	v_sub_co_u32_e64 v1, s[0:1], s49, 1
	s_nop 0
	v_readfirstlane_b32 s33, v1
	s_and_b32 s33, s33, 1
	s_mul_i32 s72, s33, 0x11000
	s_add_i32 s72, s72, 0
	s_and_b64 vcc, exec, s[0:1]
	s_cbranch_vccnz .LBB0_813
	v_add3_u32 v1, s72, v141, v145
	ds_read_b128 v[184:187], v1
	ds_read_b128 v[188:191], v1 offset:32
	ds_read_b128 v[192:195], v1 offset:8704
	ds_read_b128 v[196:199], v1 offset:8736
	ds_read_b128 v[200:203], v1 offset:64
	ds_read_b128 v[204:207], v1 offset:96
	ds_read_b128 v[228:231], v1 offset:8768
	ds_read_b128 v[232:235], v1 offset:8800
	ds_read_b128 v[236:239], v1 offset:128
	ds_read_b128 v[240:243], v1 offset:160
	ds_read_b128 v[244:247], v1 offset:8832
	ds_read_b128 v[248:251], v1 offset:8864
	v_cvt_pk_bf16_f32 v84, v52, v53
	v_cvt_pk_bf16_f32 v85, v54, v55
	v_cvt_pk_bf16_f32 v86, v56, v57
	v_cvt_pk_bf16_f32 v87, v58, v59
	v_cvt_pk_bf16_f32 v100, v60, v61
	v_cvt_pk_bf16_f32 v101, v62, v63
	v_cvt_pk_bf16_f32 v102, v64, v65
	s_waitcnt lgkmcnt(11)
	v_mfma_f32_32x32x16_bf16 v[68:83], v[184:187], v[84:87], 0
	ds_read_b128 v[184:187], v1 offset:192
	v_cvt_pk_bf16_f32 v103, v66, v67
	s_mul_i32 vcc_lo, s33, 0xa00
	s_waitcnt lgkmcnt(11)
	v_mfma_f32_32x32x16_bf16 v[68:83], v[188:191], v[100:103], v[68:83]
	ds_read_b128 v[188:191], v1 offset:224
	global_load_dwordx4 v[116:119], v[134:135], off offset:16
	global_load_dwordx4 v[120:123], v[134:135], off
	global_load_dwordx4 v[124:127], v[134:135], off offset:-16
	global_load_dwordx4 v[128:131], v[134:135], off offset:-32
	s_waitcnt lgkmcnt(11)
	v_mfma_f32_32x32x16_bf16 v[84:99], v[192:195], v[84:87], 0
	ds_read_b128 v[192:195], v1 offset:8896
	s_waitcnt lgkmcnt(11)
	v_mfma_f32_32x32x16_bf16 v[84:99], v[196:199], v[100:103], v[84:99]
	ds_read_b128 v[196:199], v1 offset:8928
	v_cvt_pk_bf16_f32 v104, v36, v37
	v_cvt_pk_bf16_f32 v105, v38, v39
	v_cvt_pk_bf16_f32 v106, v40, v41
	v_cvt_pk_bf16_f32 v107, v42, v43
	v_cvt_pk_bf16_f32 v108, v44, v45
	v_cvt_pk_bf16_f32 v109, v46, v47
	v_cvt_pk_bf16_f32 v110, v48, v49
	v_cvt_pk_bf16_f32 v111, v50, v51
	s_waitcnt lgkmcnt(11)
	v_mfma_f32_32x32x16_bf16 v[68:83], v[200:203], v[104:107], v[68:83]
	s_waitcnt lgkmcnt(10)
	v_mfma_f32_32x32x16_bf16 v[68:83], v[204:207], v[108:111], v[68:83]
	s_waitcnt lgkmcnt(9)
	v_mfma_f32_32x32x16_bf16 v[84:99], v[228:231], v[104:107], v[84:99]
	s_waitcnt lgkmcnt(8)
	v_mfma_f32_32x32x16_bf16 v[84:99], v[232:235], v[108:111], v[84:99]
	v_cvt_pk_bf16_f32 v104, v20, v21
	v_cvt_pk_bf16_f32 v105, v22, v23
	v_cvt_pk_bf16_f32 v106, v24, v25
	v_cvt_pk_bf16_f32 v107, v26, v27
	v_cvt_pk_bf16_f32 v108, v28, v29
	v_cvt_pk_bf16_f32 v109, v30, v31
	v_cvt_pk_bf16_f32 v110, v32, v33
	v_cvt_pk_bf16_f32 v111, v34, v35
	s_waitcnt lgkmcnt(7)
	v_mfma_f32_32x32x16_bf16 v[68:83], v[236:239], v[104:107], v[68:83]
	s_waitcnt lgkmcnt(6)
	v_mfma_f32_32x32x16_bf16 v[68:83], v[240:243], v[108:111], v[68:83]
	s_waitcnt lgkmcnt(5)
	v_mfma_f32_32x32x16_bf16 v[84:99], v[244:247], v[104:107], v[84:99]
	s_waitcnt lgkmcnt(4)
	v_mfma_f32_32x32x16_bf16 v[84:99], v[248:251], v[108:111], v[84:99]
	v_cvt_pk_bf16_f32 v104, v4, v5
	v_cvt_pk_bf16_f32 v105, v6, v7
	v_cvt_pk_bf16_f32 v106, v8, v9
	v_cvt_pk_bf16_f32 v107, v10, v11
	v_cvt_pk_bf16_f32 v108, v12, v13
	v_cvt_pk_bf16_f32 v109, v14, v15
	v_cvt_pk_bf16_f32 v110, v16, v17
	v_cvt_pk_bf16_f32 v111, v18, v19
	s_waitcnt lgkmcnt(3)
	v_mfma_f32_32x32x16_bf16 v[68:83], v[184:187], v[104:107], v[68:83]
	s_waitcnt lgkmcnt(2)
	v_mfma_f32_32x32x16_bf16 v[68:83], v[188:191], v[108:111], v[68:83]
	s_waitcnt lgkmcnt(1)
	v_mfma_f32_32x32x16_bf16 v[84:99], v[192:195], v[104:107], v[84:99]
	s_waitcnt lgkmcnt(0)
	v_mfma_f32_32x32x16_bf16 v[84:99], v[196:199], v[108:111], v[84:99]
	v_add3_u32 v3, s72, v145, v141
	ds_read_b128 v[200:203], v3 offset:34816
	ds_read_b128 v[204:207], v3 offset:17408
	ds_read_b128 v[228:231], v3 offset:17440
	ds_read_b128 v[232:235], v3 offset:34848
	ds_read_b128 v[236:239], v3 offset:34880
	ds_read_b128 v[240:243], v3 offset:17472
	ds_read_b128 v[244:247], v3 offset:34912
	ds_read_b128 v[248:251], v3 offset:17504
	ds_read_b128 v[184:187], v3 offset:34944
	ds_read_b128 v[188:191], v3 offset:17536
	ds_read_b128 v[192:195], v3 offset:34976
	ds_read_b128 v[196:199], v3 offset:17568
	v_add_u32_e32 v1, s72, v144
	v_add_u32_e32 v2, v1, v143
	s_waitcnt lgkmcnt(10)
	v_mfma_f32_32x32x16_bf16 v[100:115], v[200:203], v[204:207], 0
	ds_read_b128 v[200:203], v3 offset:35008
	ds_read_b128 v[204:207], v3 offset:17600
	s_waitcnt lgkmcnt(10)
	v_mfma_f32_32x32x16_bf16 v[100:115], v[232:235], v[228:231], v[100:115]
	ds_read_b128 v[228:231], v3 offset:35040
	ds_read_b128 v[232:235], v3 offset:17632
	s_waitcnt lgkmcnt(10)
	v_mfma_f32_32x32x16_bf16 v[100:115], v[236:239], v[240:243], v[100:115]
	s_waitcnt lgkmcnt(8)
	v_mfma_f32_32x32x16_bf16 v[100:115], v[244:247], v[248:251], v[100:115]
	s_waitcnt lgkmcnt(6)
	v_mfma_f32_32x32x16_bf16 v[100:115], v[184:187], v[188:191], v[100:115]
	s_waitcnt lgkmcnt(4)
	v_mfma_f32_32x32x16_bf16 v[100:115], v[192:195], v[196:199], v[100:115]
	s_waitcnt lgkmcnt(2)
	v_mfma_f32_32x32x16_bf16 v[100:115], v[200:203], v[204:207], v[100:115]
	s_waitcnt lgkmcnt(0)
	v_mfma_f32_32x32x16_bf16 v[100:115], v[228:231], v[232:235], v[100:115]
	s_nop 11
	v_cndmask_b32_e64 v167, v100, 0, s[36:37]
	v_cndmask_b32_e64 v100, v167, v100, s[34:35]
	v_cndmask_b32_e64 v101, 0, v101, s[34:35]
	v_cndmask_b32_e64 v102, v102, 0, s[30:31]
	v_cndmask_b32_e64 v103, v103, 0, s[28:29]
	v_cndmask_b32_e64 v104, v104, 0, s[26:27]
	v_cndmask_b32_e64 v105, v105, 0, s[24:25]
	v_cndmask_b32_e64 v106, v106, 0, s[22:23]
	v_cndmask_b32_e64 v107, v107, 0, s[20:21]
	v_add_u32_e32 v167, v2, v146
	ds_read_b64_tr_b16 v[236:237], v167 offset:52224
	ds_read_b64_tr_b16 v[238:239], v167 offset:54272
	ds_read_b64_tr_b16 v[240:241], v167 offset:56320
	ds_read_b64_tr_b16 v[242:243], v167 offset:58368
	ds_read_b128 v[244:247], v3 offset:34816
	ds_read_b128 v[248:251], v3 offset:26112
	ds_read_b128 v[184:187], v3 offset:34848
	ds_read_b128 v[188:191], v3 offset:26144
	ds_read_b128 v[192:195], v3 offset:34880
	ds_read_b128 v[196:199], v3 offset:26176
	ds_read_b128 v[200:203], v3 offset:34912
	ds_read_b128 v[204:207], v3 offset:26208
	v_cvt_pk_bf16_f32 v100, v100, v101
	v_cvt_pk_bf16_f32 v101, v102, v103
	v_cvt_pk_bf16_f32 v102, v104, v105
	v_cvt_pk_bf16_f32 v103, v106, v107
	s_waitcnt lgkmcnt(10)
	v_mfma_f32_32x32x16_bf16 v[68:83], v[100:103], v[236:239], v[68:83]
	ds_read_b128 v[228:231], v3 offset:34944
	ds_read_b128 v[232:235], v3 offset:26240
	v_cndmask_b32_e64 v108, v108, 0, s[18:19]
	v_cndmask_b32_e64 v109, v109, 0, s[16:17]
	v_cndmask_b32_e64 v110, v110, 0, s[14:15]
	v_cndmask_b32_e64 v111, v111, 0, s[12:13]
	v_cndmask_b32_e64 v112, v112, 0, s[10:11]
	v_cndmask_b32_e64 v113, v113, 0, s[8:9]
	v_cndmask_b32_e64 v114, v114, 0, s[6:7]
	v_cndmask_b32_e64 v115, v115, 0, s[4:5]
	v_cvt_pk_bf16_f32 v100, v108, v109
	v_cvt_pk_bf16_f32 v101, v110, v111
	v_cvt_pk_bf16_f32 v102, v112, v113
	v_cvt_pk_bf16_f32 v103, v114, v115
	s_waitcnt lgkmcnt(10)
	v_mfma_f32_32x32x16_bf16 v[68:83], v[100:103], v[240:243], v[68:83]
	ds_read_b128 v[236:239], v3 offset:34976
	ds_read_b128 v[240:243], v3 offset:26272
	v_add_u32_e32 v180, 0xcc00, v167
	s_waitcnt lgkmcnt(10)
	v_mfma_f32_32x32x16_bf16 v[100:115], v[244:247], v[248:251], 0
	ds_read_b128 v[244:247], v3 offset:35008
	ds_read_b128 v[248:251], v3 offset:26304
	s_waitcnt lgkmcnt(10)
	v_mfma_f32_32x32x16_bf16 v[100:115], v[184:187], v[188:191], v[100:115]
	ds_read_b128 v[184:187], v3 offset:35040
	ds_read_b128 v[188:191], v3 offset:26336
	s_waitcnt lgkmcnt(10)
	v_mfma_f32_32x32x16_bf16 v[100:115], v[192:195], v[196:199], v[100:115]
	ds_read_b64_tr_b16 v[192:193], v167 offset:52224
	ds_read_b64_tr_b16 v[194:195], v167 offset:54272
	s_waitcnt lgkmcnt(10)
	v_mfma_f32_32x32x16_bf16 v[100:115], v[200:203], v[204:207], v[100:115]
	ds_read_b64_tr_b16 v[196:197], v167 offset:56320
	ds_read_b64_tr_b16 v[198:199], v167 offset:58368
	s_waitcnt lgkmcnt(10)
	v_mfma_f32_32x32x16_bf16 v[100:115], v[228:231], v[232:235], v[100:115]
	ds_read_b128 v[200:203], v3 offset:43520
	ds_read_b128 v[204:207], v3 offset:26112
	s_waitcnt lgkmcnt(10)
	v_mfma_f32_32x32x16_bf16 v[100:115], v[236:239], v[240:243], v[100:115]
	ds_read_b128 v[228:231], v3 offset:43552
	ds_read_b128 v[232:235], v3 offset:26144
	s_waitcnt lgkmcnt(10)
	v_mfma_f32_32x32x16_bf16 v[100:115], v[244:247], v[248:251], v[100:115]
	ds_read_b128 v[236:239], v3 offset:43584
	ds_read_b128 v[240:243], v3 offset:26176
	s_waitcnt lgkmcnt(10)
	v_mfma_f32_32x32x16_bf16 v[100:115], v[184:187], v[188:191], v[100:115]
	ds_read_b128 v[244:247], v3 offset:43616
	ds_read_b128 v[248:251], v3 offset:26208
	s_nop 9
	v_cvt_pk_bf16_f32 v100, v100, v101
	v_cvt_pk_bf16_f32 v101, v102, v103
	v_cvt_pk_bf16_f32 v102, v104, v105
	v_cvt_pk_bf16_f32 v103, v106, v107
	s_waitcnt lgkmcnt(10)
	v_mfma_f32_32x32x16_bf16 v[84:99], v[100:103], v[192:195], v[84:99]
	ds_read_b128 v[184:187], v3 offset:43648
	ds_read_b128 v[188:191], v3 offset:26240
	v_cvt_pk_bf16_f32 v100, v108, v109
	v_cvt_pk_bf16_f32 v101, v110, v111
	v_cvt_pk_bf16_f32 v102, v112, v113
	v_cvt_pk_bf16_f32 v103, v114, v115
	s_nop 0
	s_waitcnt lgkmcnt(10)
	v_mfma_f32_32x32x16_bf16 v[84:99], v[100:103], v[196:199], v[84:99]
	ds_read_b128 v[192:195], v3 offset:43680
	ds_read_b128 v[196:199], v3 offset:26272
	s_waitcnt lgkmcnt(10)
	v_mfma_f32_32x32x16_bf16 v[100:115], v[200:203], v[204:207], 0
	ds_read_b128 v[200:203], v3 offset:43712
	ds_read_b128 v[204:207], v3 offset:26304
	s_waitcnt lgkmcnt(10)
	v_mfma_f32_32x32x16_bf16 v[100:115], v[228:231], v[232:235], v[100:115]
	ds_read_b128 v[228:231], v3 offset:43744
	ds_read_b128 v[232:235], v3 offset:26336
	s_waitcnt lgkmcnt(10)
	v_mfma_f32_32x32x16_bf16 v[100:115], v[236:239], v[240:243], v[100:115]
	ds_read_b64_tr_b16 v[236:237], v167 offset:60416
	ds_read_b64_tr_b16 v[238:239], v167 offset:62464
	s_waitcnt lgkmcnt(10)
	v_mfma_f32_32x32x16_bf16 v[100:115], v[244:247], v[248:251], v[100:115]
	ds_read_b64_tr_b16 v[240:241], v167 offset:64512
	ds_read_b64_tr_b16 v[242:243], v180 offset:14336
	s_waitcnt lgkmcnt(10)
	v_mfma_f32_32x32x16_bf16 v[100:115], v[184:187], v[188:191], v[100:115]
	s_waitcnt lgkmcnt(8)
	v_mfma_f32_32x32x16_bf16 v[100:115], v[192:195], v[196:199], v[100:115]
	s_waitcnt lgkmcnt(6)
	v_mfma_f32_32x32x16_bf16 v[100:115], v[200:203], v[204:207], v[100:115]
	s_waitcnt lgkmcnt(4)
	v_mfma_f32_32x32x16_bf16 v[100:115], v[228:231], v[232:235], v[100:115]
	s_nop 11
	v_cndmask_b32_e64 v3, v100, 0, s[36:37]
	v_cndmask_b32_e64 v168, 0, v101, s[34:35]
	v_cndmask_b32_e64 v101, v102, 0, s[30:31]
	v_cndmask_b32_e64 v102, v103, 0, s[28:29]
	v_cndmask_b32_e64 v103, v104, 0, s[26:27]
	v_cndmask_b32_e64 v104, v105, 0, s[24:25]
	v_cndmask_b32_e64 v105, v106, 0, s[22:23]
	v_cndmask_b32_e64 v106, v107, 0, s[20:21]
	v_cndmask_b32_e64 v3, v3, v100, s[34:35]
	v_cvt_pk_bf16_f32 v101, v101, v102
	v_cvt_pk_bf16_f32 v102, v103, v104
	v_cvt_pk_bf16_f32 v103, v105, v106
	v_cvt_pk_bf16_f32 v100, v3, v168
	v_cndmask_b32_e64 v107, v108, 0, s[18:19]
	v_cndmask_b32_e64 v108, v109, 0, s[16:17]
	s_waitcnt lgkmcnt(2)
	v_mfma_f32_32x32x16_bf16 v[84:99], v[100:103], v[236:239], v[84:99]
	v_cndmask_b32_e64 v109, v110, 0, s[14:15]
	v_cndmask_b32_e64 v110, v111, 0, s[12:13]
	v_cndmask_b32_e64 v111, v112, 0, s[10:11]
	v_cndmask_b32_e64 v112, v113, 0, s[8:9]
	v_cndmask_b32_e64 v3, v114, 0, s[6:7]
	v_cndmask_b32_e64 v113, v115, 0, s[4:5]
	v_cvt_pk_bf16_f32 v104, v107, v108
	v_cvt_pk_bf16_f32 v105, v109, v110
	v_cvt_pk_bf16_f32 v106, v111, v112
	v_cvt_pk_bf16_f32 v107, v3, v113
	s_waitcnt lgkmcnt(0)
	v_mfma_f32_32x32x16_bf16 v[84:99], v[104:107], v[240:243], v[84:99]
	v_add_u32_e32 v3, vcc_lo, v166
	ds_read_b128 v[244:247], v3 offset:2048
	ds_read_b128 v[248:251], v3 offset:2080
	ds_read_b128 v[184:187], v3 offset:2112
	ds_read_b128 v[188:191], v3 offset:2144
	ds_read_b128 v[192:195], v3 offset:2176
	ds_read_b128 v[196:199], v3 offset:2208
	ds_read_b128 v[200:203], v3 offset:2240
	ds_read_b128 v[204:207], v3 offset:2272
	ds_read_b128 v[228:231], v3 offset:2304
	ds_read_b128 v[232:235], v3 offset:2336
	ds_read_b128 v[236:239], v3 offset:2368
	ds_read_b128 v[240:243], v3 offset:2400
	s_waitcnt lgkmcnt(11)
	v_pk_mul_f32 v[54:55], v[54:55], v[246:247]
	s_waitcnt lgkmcnt(10)
	v_pk_mul_f32 v[56:57], v[56:57], v[248:249]
	s_waitcnt lgkmcnt(9)
	v_pk_mul_f32 v[60:61], v[60:61], v[184:185]
	s_waitcnt lgkmcnt(8)
	v_pk_mul_f32 v[64:65], v[64:65], v[188:189]
	v_pk_mul_f32 v[66:67], v[66:67], v[190:191]
	ds_read_b128 v[188:191], v3 offset:2432
	v_pk_mul_f32 v[62:63], v[62:63], v[186:187]
	ds_read_b128 v[184:187], v3 offset:2464
	v_pk_mul_f32 v[58:59], v[58:59], v[250:251]
	ds_read_b128 v[248:251], v3 offset:2496
	v_pk_mul_f32 v[52:53], v[52:53], v[244:245]
	ds_read_b128 v[244:247], v3 offset:2528
	s_waitcnt lgkmcnt(11)
	v_pk_mul_f32 v[38:39], v[38:39], v[194:195]
	s_waitcnt lgkmcnt(10)
	v_pk_mul_f32 v[40:41], v[40:41], v[196:197]
	s_waitcnt lgkmcnt(9)
	v_pk_mul_f32 v[44:45], v[44:45], v[200:201]
	s_waitcnt lgkmcnt(8)
	v_pk_mul_f32 v[48:49], v[48:49], v[204:205]
	v_pk_mul_f32 v[50:51], v[50:51], v[206:207]
	v_pk_mul_f32 v[46:47], v[46:47], v[202:203]
	v_pk_mul_f32 v[42:43], v[42:43], v[198:199]
	v_pk_mul_f32 v[36:37], v[36:37], v[192:193]
	s_waitcnt lgkmcnt(7)
	v_pk_mul_f32 v[22:23], v[22:23], v[230:231]
	s_waitcnt lgkmcnt(6)
	v_pk_mul_f32 v[24:25], v[24:25], v[232:233]
	s_waitcnt lgkmcnt(5)
	v_pk_mul_f32 v[28:29], v[28:29], v[236:237]
	s_waitcnt lgkmcnt(4)
	v_pk_mul_f32 v[32:33], v[32:33], v[240:241]
	v_pk_mul_f32 v[34:35], v[34:35], v[242:243]
	v_pk_mul_f32 v[30:31], v[30:31], v[238:239]
	v_pk_mul_f32 v[26:27], v[26:27], v[234:235]
	v_pk_mul_f32 v[20:21], v[20:21], v[228:229]
	v_add_u32_e32 v3, v2, v147
	ds_read_b64_tr_b16 v[204:205], v3 offset:52224
	s_waitcnt lgkmcnt(4)
	v_pk_mul_f32 v[4:5], v[4:5], v[188:189]
	s_waitcnt lgkmcnt(3)
	v_pk_mul_f32 v[10:11], v[10:11], v[186:187]
	s_waitcnt lgkmcnt(2)
	v_pk_mul_f32 v[12:13], v[12:13], v[248:249]
	v_add_u32_e32 v108, v1, v150
	v_pk_mul_f32 v[14:15], v[14:15], v[250:251]
	v_add_u32_e32 v110, v108, v142
	ds_read_b64_tr_b16 v[202:203], v110 offset:34816
	v_add_u32_e32 v3, v2, v148
	ds_read_b64_tr_b16 v[206:207], v3 offset:52224
	v_pk_mul_f32 v[6:7], v[6:7], v[190:191]
	v_add_u32_e32 v3, v1, v149
	v_add_u32_e32 v109, v3, v142
	ds_read_b64_tr_b16 v[200:201], v109 offset:34816
	v_pk_mul_f32 v[8:9], v[8:9], v[184:185]
	s_waitcnt lgkmcnt(0)
	v_mfma_f32_32x32x16_bf16 v[52:67], v[200:203], v[204:207], v[52:67]
	v_add_u32_e32 v104, v3, v151
	ds_read_b64_tr_b16 v[196:197], v104 offset:34816
	v_add_u32_e32 v106, v108, v151
	ds_read_b64_tr_b16 v[198:199], v106 offset:34816
	ds_read_b64_tr_b16 v[192:193], v109 offset:34944
	ds_read_b64_tr_b16 v[194:195], v110 offset:34944
	v_add_u32_e32 v3, v3, v152
	ds_read_b64_tr_b16 v[240:241], v3 offset:34816
	v_pk_mul_f32 v[16:17], v[16:17], v[244:245]
	v_pk_mul_f32 v[18:19], v[18:19], v[246:247]
	s_waitcnt lgkmcnt(3)
	v_mfma_f32_32x32x16_bf16 v[36:51], v[196:199], v[204:207], v[36:51]
	s_waitcnt lgkmcnt(1)
	v_mfma_f32_32x32x16_bf16 v[20:35], v[192:195], v[204:207], v[20:35]
	v_add_u32_e32 v3, v108, v152
	ds_read_b64_tr_b16 v[242:243], v3 offset:34816
	s_waitcnt lgkmcnt(0)
	v_mfma_f32_32x32x16_bf16 v[4:19], v[240:243], v[204:207], v[4:19]
	v_add_u32_e32 v108, v1, v156
	v_add_u32_e32 v3, v2, v153
	ds_read_b64_tr_b16 v[236:237], v3 offset:52224
	v_add_u32_e32 v110, v108, v142
	ds_read_b64_tr_b16 v[234:235], v110 offset:34816
	v_add_u32_e32 v3, v2, v154
	ds_read_b64_tr_b16 v[238:239], v3 offset:52224
	v_add_u32_e32 v3, v1, v155
	v_add_u32_e32 v109, v3, v142
	ds_read_b64_tr_b16 v[232:233], v109 offset:34816
	s_waitcnt lgkmcnt(0)
	v_mfma_f32_32x32x16_bf16 v[52:67], v[232:235], v[236:239], v[52:67]
	v_add_u32_e32 v104, v3, v151
	ds_read_b64_tr_b16 v[228:229], v104 offset:34816
	v_add_u32_e32 v106, v108, v151
	ds_read_b64_tr_b16 v[230:231], v106 offset:34816
	ds_read_b64_tr_b16 v[248:249], v109 offset:34944
	ds_read_b64_tr_b16 v[250:251], v110 offset:34944
	v_add_u32_e32 v3, v3, v152
	ds_read_b64_tr_b16 v[188:189], v3 offset:34816
	s_waitcnt lgkmcnt(3)
	v_mfma_f32_32x32x16_bf16 v[36:51], v[228:231], v[236:239], v[36:51]
	s_waitcnt lgkmcnt(1)
	v_mfma_f32_32x32x16_bf16 v[20:35], v[248:251], v[236:239], v[20:35]
	v_add_u32_e32 v3, v108, v152
	ds_read_b64_tr_b16 v[190:191], v3 offset:34816
	s_waitcnt lgkmcnt(0)
	v_mfma_f32_32x32x16_bf16 v[4:19], v[188:191], v[236:239], v[4:19]
	v_add_u32_e32 v108, v1, v160
	v_add_u32_e32 v3, v2, v157
	ds_read_b64_tr_b16 v[184:185], v3 offset:52224
	v_add_u32_e32 v110, v108, v142
	ds_read_b64_tr_b16 v[202:203], v110 offset:34816
	v_add_u32_e32 v3, v2, v158
	ds_read_b64_tr_b16 v[186:187], v3 offset:52224
	v_add_u32_e32 v3, v1, v159
	v_add_u32_e32 v109, v3, v142
	ds_read_b64_tr_b16 v[200:201], v109 offset:34816
	s_waitcnt lgkmcnt(0)
	v_mfma_f32_32x32x16_bf16 v[52:67], v[200:203], v[184:187], v[52:67]
	v_add_u32_e32 v104, v3, v151
	ds_read_b64_tr_b16 v[244:245], v104 offset:34816
	v_add_u32_e32 v106, v108, v151
	ds_read_b64_tr_b16 v[246:247], v106 offset:34816
	ds_read_b64_tr_b16 v[196:197], v109 offset:34944
	ds_read_b64_tr_b16 v[198:199], v110 offset:34944
	v_add_u32_e32 v3, v3, v152
	ds_read_b64_tr_b16 v[192:193], v3 offset:34816
	s_waitcnt lgkmcnt(3)
	v_mfma_f32_32x32x16_bf16 v[36:51], v[244:247], v[184:187], v[36:51]
	s_waitcnt lgkmcnt(1)
	v_mfma_f32_32x32x16_bf16 v[20:35], v[196:199], v[184:187], v[20:35]
	v_add_u32_e32 v3, v108, v152
	ds_read_b64_tr_b16 v[194:195], v3 offset:34816
	s_waitcnt lgkmcnt(0)
	v_mfma_f32_32x32x16_bf16 v[4:19], v[192:195], v[184:187], v[4:19]
	v_add_u32_e32 v3, v2, v161
	ds_read_b64_tr_b16 v[204:205], v3 offset:52224
	v_add_u32_e32 v2, v2, v162
	ds_read_b64_tr_b16 v[206:207], v2 offset:52224
	v_add_u32_e32 v2, v1, v163
	v_add_u32_e32 v1, v1, v164
	v_add_u32_e32 v3, v2, v142
	ds_read_b64_tr_b16 v[240:241], v3 offset:34816
	v_add_u32_e32 v108, v1, v142
	ds_read_b64_tr_b16 v[242:243], v108 offset:34816
	s_waitcnt lgkmcnt(0)
	v_mfma_f32_32x32x16_bf16 v[52:67], v[240:243], v[204:207], v[52:67]
	v_add_u32_e32 v104, v2, v151
	ds_read_b64_tr_b16 v[232:233], v104 offset:34816
	v_add_u32_e32 v106, v1, v151
	ds_read_b64_tr_b16 v[234:235], v106 offset:34816
	ds_read_b64_tr_b16 v[228:229], v3 offset:34944
	ds_read_b64_tr_b16 v[230:231], v108 offset:34944
	v_add_u32_e32 v2, v2, v152
	ds_read_b64_tr_b16 v[248:249], v2 offset:34816
	v_add_u32_e32 v1, v1, v152
	ds_read_b64_tr_b16 v[250:251], v1 offset:34816
	s_waitcnt lgkmcnt(4)
	v_mfma_f32_32x32x16_bf16 v[36:51], v[232:235], v[204:207], v[36:51]
	s_waitcnt lgkmcnt(2)
	v_mfma_f32_32x32x16_bf16 v[20:35], v[228:231], v[204:207], v[20:35]
	s_waitcnt lgkmcnt(0)
	v_mfma_f32_32x32x16_bf16 v[4:19], v[248:251], v[204:207], v[4:19]

.Lpg8skip8:
	s_waitcnt lgkmcnt(0)
	s_barrier
	s_setprio 1
	s_waitcnt lgkmcnt(0)
	v_mfma_f32_16x16x32_bf16 v[124:127], v[156:159], v[188:191], v[124:127]
	v_mfma_f32_16x16x32_bf16 v[120:123], v[164:167], v[188:191], v[120:123]
	v_mfma_f32_16x16x32_bf16 v[108:111], v[156:159], v[196:199], v[108:111]
	v_mfma_f32_16x16x32_bf16 v[104:107], v[164:167], v[196:199], v[104:107]
	v_mfma_f32_16x16x32_bf16 v[92:95], v[156:159], v[204:207], v[92:95]
	v_mfma_f32_16x16x32_bf16 v[88:91], v[164:167], v[204:207], v[88:91]
	v_mfma_f32_16x16x32_bf16 v[76:79], v[156:159], v[216:219], v[76:79]
	v_mfma_f32_16x16x32_bf16 v[72:75], v[164:167], v[216:219], v[72:75]
	v_mfma_f32_16x16x32_bf16 v[124:127], v[160:163], v[192:195], v[124:127]
	v_mfma_f32_16x16x32_bf16 v[120:123], v[168:171], v[192:195], v[120:123]
	v_mfma_f32_16x16x32_bf16 v[108:111], v[160:163], v[200:203], v[108:111]
	v_mfma_f32_16x16x32_bf16 v[104:107], v[168:171], v[200:203], v[104:107]
	v_mfma_f32_16x16x32_bf16 v[92:95], v[160:163], v[212:215], v[92:95]
	v_mfma_f32_16x16x32_bf16 v[88:91], v[168:171], v[212:215], v[88:91]
	v_mfma_f32_16x16x32_bf16 v[76:79], v[160:163], v[220:223], v[76:79]
	v_mfma_f32_16x16x32_bf16 v[72:75], v[168:171], v[220:223], v[72:75]
	s_setprio 0
	s_setprio 1
	v_mfma_f32_16x16x32_bf16 v[116:119], v[172:175], v[188:191], v[116:119]
	v_mfma_f32_16x16x32_bf16 v[112:115], v[180:183], v[188:191], v[112:115]
	v_mfma_f32_16x16x32_bf16 v[100:103], v[172:175], v[196:199], v[100:103]
	v_mfma_f32_16x16x32_bf16 v[96:99], v[180:183], v[196:199], v[96:99]
	v_mfma_f32_16x16x32_bf16 v[84:87], v[172:175], v[204:207], v[84:87]
	v_mfma_f32_16x16x32_bf16 v[80:83], v[180:183], v[204:207], v[80:83]
	v_mfma_f32_16x16x32_bf16 v[68:71], v[172:175], v[216:219], v[68:71]
	v_mfma_f32_16x16x32_bf16 v[64:67], v[180:183], v[216:219], v[64:67]
	v_mfma_f32_16x16x32_bf16 v[116:119], v[176:179], v[192:195], v[116:119]
	v_mfma_f32_16x16x32_bf16 v[112:115], v[184:187], v[192:195], v[112:115]
	v_mfma_f32_16x16x32_bf16 v[100:103], v[176:179], v[200:203], v[100:103]
	v_mfma_f32_16x16x32_bf16 v[96:99], v[184:187], v[200:203], v[96:99]
	v_mfma_f32_16x16x32_bf16 v[84:87], v[176:179], v[212:215], v[84:87]
	v_mfma_f32_16x16x32_bf16 v[80:83], v[184:187], v[212:215], v[80:83]
	v_mfma_f32_16x16x32_bf16 v[68:71], v[176:179], v[220:223], v[68:71]
	v_mfma_f32_16x16x32_bf16 v[64:67], v[184:187], v[220:223], v[64:67]
	s_setprio 0
	s_barrier
	s_add_i32 s75, s55, s44
	s_add_u32 s98, s34, s12
	s_addc_u32 s99, s35, s13
	s_mov_b32 m0, s75
	ds_read_b128 v[188:191], v154 offset:16384
	ds_read_b128 v[192:195], v154 offset:17408
	ds_read_b128 v[196:199], v154 offset:18432
	ds_read_b128 v[200:203], v154 offset:19456
	ds_read_b128 v[204:207], v154 offset:20480
	ds_read_b128 v[212:215], v154 offset:21504
	ds_read_b128 v[216:219], v154 offset:22528
	ds_read_b128 v[220:223], v154 offset:23552
	global_load_lds_dwordx4 v132, s[34:35]
	s_add_i32 m0, s75, 0x2000
	s_add_u32 s76, s34, 0x40000
	s_addc_u32 s77, s35, 0
	s_add_i32 s75, s56, s44
	global_load_lds_dwordx4 v128, s[34:35]
	s_mov_b32 m0, s75
	s_nop 0
	global_load_lds_dwordx4 v132, s[76:77]
	s_add_i32 m0, s75, 0x2000
	s_nop 0
	global_load_lds_dwordx4 v128, s[76:77]
	s_add_u32 s100, s36, s12
	s_addc_u32 s101, s37, s13
	s_mov_b32 m0, s25
	s_nop 0
	global_load_lds_dwordx4 v134, s[36:37]
	s_mov_b32 m0, s46
	s_nop 0
	global_load_lds_dwordx4 v130, s[36:37]
	s_cmp_lg_u32 s33, 0
	s_cbranch_scc1 .Lpg8skip9
	s_waitcnt vmcnt(8)
.Lpg8skip9:
	s_waitcnt lgkmcnt(0)
	s_barrier
	s_setprio 1
	s_waitcnt lgkmcnt(0)
	v_mfma_f32_16x16x32_bf16 v[60:63], v[156:159], v[188:191], v[60:63]
	v_mfma_f32_16x16x32_bf16 v[56:59], v[164:167], v[188:191], v[56:59]
	v_mfma_f32_16x16x32_bf16 v[44:47], v[156:159], v[196:199], v[44:47]
	v_mfma_f32_16x16x32_bf16 v[40:43], v[164:167], v[196:199], v[40:43]
	v_mfma_f32_16x16x32_bf16 v[28:31], v[156:159], v[204:207], v[28:31]
	v_mfma_f32_16x16x32_bf16 v[24:27], v[164:167], v[204:207], v[24:27]
	v_mfma_f32_16x16x32_bf16 v[12:15], v[156:159], v[216:219], v[12:15]
	v_mfma_f32_16x16x32_bf16 v[8:11], v[164:167], v[216:219], v[8:11]
	v_mfma_f32_16x16x32_bf16 v[60:63], v[160:163], v[192:195], v[60:63]
	v_mfma_f32_16x16x32_bf16 v[56:59], v[168:171], v[192:195], v[56:59]
	v_mfma_f32_16x16x32_bf16 v[44:47], v[160:163], v[200:203], v[44:47]
	v_mfma_f32_16x16x32_bf16 v[40:43], v[168:171], v[200:203], v[40:43]
	v_mfma_f32_16x16x32_bf16 v[28:31], v[160:163], v[212:215], v[28:31]
	v_mfma_f32_16x16x32_bf16 v[24:27], v[168:171], v[212:215], v[24:27]
	v_mfma_f32_16x16x32_bf16 v[12:15], v[160:163], v[220:223], v[12:15]
	v_mfma_f32_16x16x32_bf16 v[8:11], v[168:171], v[220:223], v[8:11]
	s_setprio 0
	s_setprio 1
	v_mfma_f32_16x16x32_bf16 v[52:55], v[172:175], v[188:191], v[52:55]
	v_mfma_f32_16x16x32_bf16 v[48:51], v[180:183], v[188:191], v[48:51]
	v_mfma_f32_16x16x32_bf16 v[36:39], v[172:175], v[196:199], v[36:39]
	v_mfma_f32_16x16x32_bf16 v[32:35], v[180:183], v[196:199], v[32:35]
	v_mfma_f32_16x16x32_bf16 v[20:23], v[172:175], v[204:207], v[20:23]
	v_mfma_f32_16x16x32_bf16 v[16:19], v[180:183], v[204:207], v[16:19]
	v_mfma_f32_16x16x32_bf16 v[4:7], v[172:175], v[216:219], v[4:7]
	v_mfma_f32_16x16x32_bf16 v[0:3], v[180:183], v[216:219], v[0:3]
	v_mfma_f32_16x16x32_bf16 v[52:55], v[176:179], v[192:195], v[52:55]
	v_mfma_f32_16x16x32_bf16 v[48:51], v[184:187], v[192:195], v[48:51]
	v_mfma_f32_16x16x32_bf16 v[36:39], v[176:179], v[200:203], v[36:39]
	v_mfma_f32_16x16x32_bf16 v[32:35], v[184:187], v[200:203], v[32:35]
	v_mfma_f32_16x16x32_bf16 v[20:23], v[176:179], v[212:215], v[20:23]
	v_mfma_f32_16x16x32_bf16 v[16:19], v[184:187], v[212:215], v[16:19]
	v_mfma_f32_16x16x32_bf16 v[4:7], v[176:179], v[220:223], v[4:7]
	v_mfma_f32_16x16x32_bf16 v[0:3], v[184:187], v[220:223], v[0:3]
	s_setprio 0
	s_barrier
	s_add_i32 s33, 0, 0x18000
	v_add_u32_e32 v155, s33, v150
	s_add_i32 s75, 0, 0x1c000
	ds_read_b128 v[156:159], v155
	ds_read_b128 v[160:163], v155 offset:1024
	ds_read_b128 v[164:167], v155 offset:2048
	ds_read_b128 v[168:171], v155 offset:3072
	v_add_u32_e32 v155, s75, v150
	ds_read_b128 v[172:175], v155
	ds_read_b128 v[176:179], v155 offset:1024
	ds_read_b128 v[180:183], v155 offset:2048
	ds_read_b128 v[184:187], v155 offset:3072
	s_add_u32 s36, s36, 0x40000
	s_addc_u32 s37, s37, 0
	s_mov_b32 m0, s47
	ds_read_b128 v[188:191], v154 offset:32768
	ds_read_b128 v[192:195], v154 offset:33792
	ds_read_b128 v[196:199], v154 offset:34816
	ds_read_b128 v[200:203], v154 offset:35840
	ds_read_b128 v[204:207], v154 offset:36864
	ds_read_b128 v[212:215], v154 offset:37888
	ds_read_b128 v[216:219], v154 offset:38912
	ds_read_b128 v[220:223], v154 offset:39936
	global_load_lds_dwordx4 v134, s[36:37]
	s_mov_b32 m0, s48
	s_nop 0
	global_load_lds_dwordx4 v130, s[36:37]
	s_waitcnt vmcnt(8)
	s_waitcnt lgkmcnt(0)
	s_barrier
	s_setprio 1
	s_waitcnt lgkmcnt(0)
	v_mfma_f32_16x16x32_bf16 v[124:127], v[156:159], v[188:191], v[124:127]
	v_mfma_f32_16x16x32_bf16 v[120:123], v[164:167], v[188:191], v[120:123]
	v_mfma_f32_16x16x32_bf16 v[108:111], v[156:159], v[196:199], v[108:111]
	v_mfma_f32_16x16x32_bf16 v[104:107], v[164:167], v[196:199], v[104:107]
	v_mfma_f32_16x16x32_bf16 v[92:95], v[156:159], v[204:207], v[92:95]
	v_mfma_f32_16x16x32_bf16 v[88:91], v[164:167], v[204:207], v[88:91]
	v_mfma_f32_16x16x32_bf16 v[76:79], v[156:159], v[216:219], v[76:79]
	v_mfma_f32_16x16x32_bf16 v[72:75], v[164:167], v[216:219], v[72:75]
	v_mfma_f32_16x16x32_bf16 v[124:127], v[160:163], v[192:195], v[124:127]
	v_mfma_f32_16x16x32_bf16 v[120:123], v[168:171], v[192:195], v[120:123]
	v_mfma_f32_16x16x32_bf16 v[108:111], v[160:163], v[200:203], v[108:111]
	v_mfma_f32_16x16x32_bf16 v[104:107], v[168:171], v[200:203], v[104:107]
	v_mfma_f32_16x16x32_bf16 v[92:95], v[160:163], v[212:215], v[92:95]
	v_mfma_f32_16x16x32_bf16 v[88:91], v[168:171], v[212:215], v[88:91]
	v_mfma_f32_16x16x32_bf16 v[76:79], v[160:163], v[220:223], v[76:79]
	v_mfma_f32_16x16x32_bf16 v[72:75], v[168:171], v[220:223], v[72:75]
	s_setprio 0
	s_setprio 1
	v_mfma_f32_16x16x32_bf16 v[116:119], v[172:175], v[188:191], v[116:119]
	v_mfma_f32_16x16x32_bf16 v[112:115], v[180:183], v[188:191], v[112:115]
	v_mfma_f32_16x16x32_bf16 v[100:103], v[172:175], v[196:199], v[100:103]
	v_mfma_f32_16x16x32_bf16 v[96:99], v[180:183], v[196:199], v[96:99]
	v_mfma_f32_16x16x32_bf16 v[84:87], v[172:175], v[204:207], v[84:87]
	v_mfma_f32_16x16x32_bf16 v[80:83], v[180:183], v[204:207], v[80:83]
	v_mfma_f32_16x16x32_bf16 v[68:71], v[172:175], v[216:219], v[68:71]
	v_mfma_f32_16x16x32_bf16 v[64:67], v[180:183], v[216:219], v[64:67]
	v_mfma_f32_16x16x32_bf16 v[116:119], v[176:179], v[192:195], v[116:119]
	v_mfma_f32_16x16x32_bf16 v[112:115], v[184:187], v[192:195], v[112:115]
	v_mfma_f32_16x16x32_bf16 v[100:103], v[176:179], v[200:203], v[100:103]
	v_mfma_f32_16x16x32_bf16 v[96:99], v[184:187], v[200:203], v[96:99]
	v_mfma_f32_16x16x32_bf16 v[84:87], v[176:179], v[212:215], v[84:87]
	v_mfma_f32_16x16x32_bf16 v[80:83], v[184:187], v[212:215], v[80:83]
	v_mfma_f32_16x16x32_bf16 v[68:71], v[176:179], v[220:223], v[68:71]
	v_mfma_f32_16x16x32_bf16 v[64:67], v[184:187], v[220:223], v[64:67]
	s_setprio 0
	s_barrier
	s_add_i32 s33, s33, s44
	s_mov_b32 m0, s33
	ds_read_b128 v[188:191], v154 offset:49152
	ds_read_b128 v[192:195], v154 offset:50176
	ds_read_b128 v[196:199], v154 offset:51200
	ds_read_b128 v[200:203], v154 offset:52224
	ds_read_b128 v[204:207], v154 offset:53248
	ds_read_b128 v[212:215], v154 offset:54272
	ds_read_b128 v[216:219], v154 offset:55296
	ds_read_b128 v[220:223], v154 offset:56320
	global_load_lds_dwordx4 v132, s[98:99]
	s_add_i32 m0, s33, 0x2000
	s_add_u32 s34, s34, 0x40080
	s_addc_u32 s35, s35, 0
	s_add_i32 s33, s75, s44
	global_load_lds_dwordx4 v128, s[98:99]
	s_mov_b32 m0, s33
	s_nop 0
	global_load_lds_dwordx4 v132, s[34:35]
	s_add_i32 m0, s33, 0x2000
	s_nop 0
	global_load_lds_dwordx4 v128, s[34:35]
	s_mov_b32 m0, s50
	s_nop 0
	global_load_lds_dwordx4 v134, s[100:101]
	s_mov_b32 m0, s51
	s_nop 0
	global_load_lds_dwordx4 v130, s[100:101]
	s_waitcnt vmcnt(8)
	s_waitcnt lgkmcnt(0)
	s_barrier
	s_setprio 1
	s_waitcnt lgkmcnt(0)
	v_mfma_f32_16x16x32_bf16 v[60:63], v[156:159], v[188:191], v[60:63]
	v_mfma_f32_16x16x32_bf16 v[56:59], v[164:167], v[188:191], v[56:59]
	v_mfma_f32_16x16x32_bf16 v[44:47], v[156:159], v[196:199], v[44:47]
	v_mfma_f32_16x16x32_bf16 v[40:43], v[164:167], v[196:199], v[40:43]
	v_mfma_f32_16x16x32_bf16 v[28:31], v[156:159], v[204:207], v[28:31]
	v_mfma_f32_16x16x32_bf16 v[24:27], v[164:167], v[204:207], v[24:27]
	v_mfma_f32_16x16x32_bf16 v[12:15], v[156:159], v[216:219], v[12:15]
	v_mfma_f32_16x16x32_bf16 v[8:11], v[164:167], v[216:219], v[8:11]
	v_mfma_f32_16x16x32_bf16 v[60:63], v[160:163], v[192:195], v[60:63]
	v_mfma_f32_16x16x32_bf16 v[56:59], v[168:171], v[192:195], v[56:59]
	v_mfma_f32_16x16x32_bf16 v[44:47], v[160:163], v[200:203], v[44:47]
	v_mfma_f32_16x16x32_bf16 v[40:43], v[168:171], v[200:203], v[40:43]
	v_mfma_f32_16x16x32_bf16 v[28:31], v[160:163], v[212:215], v[28:31]
	v_mfma_f32_16x16x32_bf16 v[24:27], v[168:171], v[212:215], v[24:27]
	v_mfma_f32_16x16x32_bf16 v[12:15], v[160:163], v[220:223], v[12:15]
	v_mfma_f32_16x16x32_bf16 v[8:11], v[168:171], v[220:223], v[8:11]
	s_setprio 0
	s_setprio 1
	v_mfma_f32_16x16x32_bf16 v[52:55], v[172:175], v[188:191], v[52:55]
	v_mfma_f32_16x16x32_bf16 v[48:51], v[180:183], v[188:191], v[48:51]
	v_mfma_f32_16x16x32_bf16 v[36:39], v[172:175], v[196:199], v[36:39]
	v_mfma_f32_16x16x32_bf16 v[32:35], v[180:183], v[196:199], v[32:35]
	v_mfma_f32_16x16x32_bf16 v[20:23], v[172:175], v[204:207], v[20:23]
	v_mfma_f32_16x16x32_bf16 v[16:19], v[180:183], v[204:207], v[16:19]
	v_mfma_f32_16x16x32_bf16 v[4:7], v[172:175], v[216:219], v[4:7]
	v_mfma_f32_16x16x32_bf16 v[0:3], v[180:183], v[216:219], v[0:3]
	v_mfma_f32_16x16x32_bf16 v[52:55], v[176:179], v[192:195], v[52:55]
	v_mfma_f32_16x16x32_bf16 v[48:51], v[184:187], v[192:195], v[48:51]
	v_mfma_f32_16x16x32_bf16 v[36:39], v[176:179], v[200:203], v[36:39]
	v_mfma_f32_16x16x32_bf16 v[32:35], v[184:187], v[200:203], v[32:35]
	v_mfma_f32_16x16x32_bf16 v[20:23], v[176:179], v[212:215], v[20:23]
	v_mfma_f32_16x16x32_bf16 v[16:19], v[184:187], v[212:215], v[16:19]
	v_mfma_f32_16x16x32_bf16 v[4:7], v[176:179], v[220:223], v[4:7]
	v_mfma_f32_16x16x32_bf16 v[0:3], v[184:187], v[220:223], v[0:3]
	s_setprio 0
	s_barrier
	s_add_i32 s74, s74, 2
	s_add_u32 s30, s30, 0x100
	s_addc_u32 s31, s31, 0
	s_cmp_gt_u32 s74, 13
	s_cbranch_scc0 .LBB0_1047
	s_and_b64 vcc, exec, s[14:15]
	s_cbranch_vccz .LBB0_1050
	s_barrier

.Lpg8skip10:
	s_waitcnt lgkmcnt(0)
	s_barrier
	s_setprio 1
	s_waitcnt lgkmcnt(0)
	v_mfma_f32_16x16x32_bf16 v[124:127], v[144:147], v[182:185], v[124:127]
	v_mfma_f32_16x16x32_bf16 v[120:123], v[158:161], v[182:185], v[120:123]
	v_mfma_f32_16x16x32_bf16 v[112:115], v[144:147], v[190:193], v[112:115]
	v_mfma_f32_16x16x32_bf16 v[108:111], v[158:161], v[190:193], v[108:111]
	v_mfma_f32_16x16x32_bf16 v[96:99], v[144:147], v[198:201], v[96:99]
	v_mfma_f32_16x16x32_bf16 v[92:95], v[158:161], v[198:201], v[92:95]
	v_mfma_f32_16x16x32_bf16 v[80:83], v[144:147], v[206:209], v[80:83]
	v_mfma_f32_16x16x32_bf16 v[76:79], v[158:161], v[206:209], v[76:79]
	v_mfma_f32_16x16x32_bf16 v[124:127], v[148:151], v[186:189], v[124:127]
	v_mfma_f32_16x16x32_bf16 v[120:123], v[162:165], v[186:189], v[120:123]
	v_mfma_f32_16x16x32_bf16 v[112:115], v[148:151], v[194:197], v[112:115]
	v_mfma_f32_16x16x32_bf16 v[108:111], v[162:165], v[194:197], v[108:111]
	v_mfma_f32_16x16x32_bf16 v[96:99], v[148:151], v[202:205], v[96:99]
	v_mfma_f32_16x16x32_bf16 v[92:95], v[162:165], v[202:205], v[92:95]
	v_mfma_f32_16x16x32_bf16 v[80:83], v[148:151], v[210:213], v[80:83]
	v_mfma_f32_16x16x32_bf16 v[76:79], v[162:165], v[210:213], v[76:79]
	s_setprio 0
	s_setprio 1
	v_mfma_f32_16x16x32_bf16 v[116:119], v[166:169], v[182:185], v[116:119]
	v_mfma_f32_16x16x32_bf16 v[104:107], v[174:177], v[182:185], v[104:107]
	v_mfma_f32_16x16x32_bf16 v[100:103], v[166:169], v[190:193], v[100:103]
	v_mfma_f32_16x16x32_bf16 v[88:91], v[174:177], v[190:193], v[88:91]
	v_mfma_f32_16x16x32_bf16 v[84:87], v[166:169], v[198:201], v[84:87]
	v_mfma_f32_16x16x32_bf16 v[72:75], v[174:177], v[198:201], v[72:75]
	v_mfma_f32_16x16x32_bf16 v[68:71], v[166:169], v[206:209], v[68:71]
	v_mfma_f32_16x16x32_bf16 v[64:67], v[174:177], v[206:209], v[64:67]
	v_mfma_f32_16x16x32_bf16 v[116:119], v[170:173], v[186:189], v[116:119]
	v_mfma_f32_16x16x32_bf16 v[104:107], v[178:181], v[186:189], v[104:107]
	v_mfma_f32_16x16x32_bf16 v[100:103], v[170:173], v[194:197], v[100:103]
	v_mfma_f32_16x16x32_bf16 v[88:91], v[178:181], v[194:197], v[88:91]
	v_mfma_f32_16x16x32_bf16 v[84:87], v[170:173], v[202:205], v[84:87]
	v_mfma_f32_16x16x32_bf16 v[72:75], v[178:181], v[202:205], v[72:75]
	v_mfma_f32_16x16x32_bf16 v[68:71], v[170:173], v[210:213], v[68:71]
	v_mfma_f32_16x16x32_bf16 v[64:67], v[178:181], v[210:213], v[64:67]
	s_setprio 0
	s_barrier
	s_add_i32 s18, s42, s28
	s_add_u32 s98, s22, s10
	s_addc_u32 s99, s23, s11
	s_mov_b32 m0, s18
	ds_read_b128 v[182:185], v157 offset:16384
	ds_read_b128 v[186:189], v157 offset:17408
	ds_read_b128 v[190:193], v157 offset:18432
	ds_read_b128 v[194:197], v157 offset:19456
	ds_read_b128 v[198:201], v157 offset:20480
	ds_read_b128 v[202:205], v157 offset:21504
	ds_read_b128 v[206:209], v157 offset:22528
	ds_read_b128 v[210:213], v157 offset:23552
	global_load_lds_dwordx4 v132, s[22:23]
	s_add_i32 m0, s18, 0x2000
	s_add_u32 s18, s22, 0xb0000
	s_addc_u32 s19, s23, 0
	s_add_i32 s53, s43, s28
	global_load_lds_dwordx4 v128, s[22:23]
	s_mov_b32 m0, s53
	s_nop 0
	global_load_lds_dwordx4 v132, s[18:19]
	s_add_i32 m0, s53, 0x2000
	s_nop 0
	global_load_lds_dwordx4 v128, s[18:19]
	s_add_u32 s100, s24, s12
	s_addc_u32 s101, s25, s13
	s_mov_b32 m0, s29
	s_nop 0
	global_load_lds_dwordx4 v134, s[24:25]
	s_mov_b32 m0, s30
	s_nop 0
	global_load_lds_dwordx4 v130, s[24:25]
	s_cmp_lg_u32 s34, 0
	s_cbranch_scc1 .Lpg8skip11
	s_waitcnt vmcnt(8)
.Lpg8skip11:
	s_waitcnt lgkmcnt(0)
	s_barrier
	s_setprio 1
	s_waitcnt lgkmcnt(0)
	v_mfma_f32_16x16x32_bf16 v[60:63], v[144:147], v[182:185], v[60:63]
	v_mfma_f32_16x16x32_bf16 v[56:59], v[158:161], v[182:185], v[56:59]
	v_mfma_f32_16x16x32_bf16 v[48:51], v[144:147], v[190:193], v[48:51]
	v_mfma_f32_16x16x32_bf16 v[44:47], v[158:161], v[190:193], v[44:47]
	v_mfma_f32_16x16x32_bf16 v[32:35], v[144:147], v[198:201], v[32:35]
	v_mfma_f32_16x16x32_bf16 v[28:31], v[158:161], v[198:201], v[28:31]
	v_mfma_f32_16x16x32_bf16 v[16:19], v[144:147], v[206:209], v[16:19]
	v_mfma_f32_16x16x32_bf16 v[12:15], v[158:161], v[206:209], v[12:15]
	v_mfma_f32_16x16x32_bf16 v[60:63], v[148:151], v[186:189], v[60:63]
	v_mfma_f32_16x16x32_bf16 v[56:59], v[162:165], v[186:189], v[56:59]
	v_mfma_f32_16x16x32_bf16 v[48:51], v[148:151], v[194:197], v[48:51]
	v_mfma_f32_16x16x32_bf16 v[44:47], v[162:165], v[194:197], v[44:47]
	v_mfma_f32_16x16x32_bf16 v[32:35], v[148:151], v[202:205], v[32:35]
	v_mfma_f32_16x16x32_bf16 v[28:31], v[162:165], v[202:205], v[28:31]
	v_mfma_f32_16x16x32_bf16 v[16:19], v[148:151], v[210:213], v[16:19]
	v_mfma_f32_16x16x32_bf16 v[12:15], v[162:165], v[210:213], v[12:15]
	s_setprio 0
	s_setprio 1
	v_mfma_f32_16x16x32_bf16 v[52:55], v[166:169], v[182:185], v[52:55]
	v_mfma_f32_16x16x32_bf16 v[40:43], v[174:177], v[182:185], v[40:43]
	v_mfma_f32_16x16x32_bf16 v[36:39], v[166:169], v[190:193], v[36:39]
	v_mfma_f32_16x16x32_bf16 v[24:27], v[174:177], v[190:193], v[24:27]
	v_mfma_f32_16x16x32_bf16 v[20:23], v[166:169], v[198:201], v[20:23]
	v_mfma_f32_16x16x32_bf16 v[8:11], v[174:177], v[198:201], v[8:11]
	v_mfma_f32_16x16x32_bf16 v[4:7], v[166:169], v[206:209], v[4:7]
	v_mfma_f32_16x16x32_bf16 v[0:3], v[174:177], v[206:209], v[0:3]
	v_mfma_f32_16x16x32_bf16 v[52:55], v[170:173], v[186:189], v[52:55]
	v_mfma_f32_16x16x32_bf16 v[40:43], v[178:181], v[186:189], v[40:43]
	v_mfma_f32_16x16x32_bf16 v[36:39], v[170:173], v[194:197], v[36:39]
	v_mfma_f32_16x16x32_bf16 v[24:27], v[178:181], v[194:197], v[24:27]
	v_mfma_f32_16x16x32_bf16 v[20:23], v[170:173], v[202:205], v[20:23]
	v_mfma_f32_16x16x32_bf16 v[8:11], v[178:181], v[202:205], v[8:11]
	v_mfma_f32_16x16x32_bf16 v[4:7], v[170:173], v[210:213], v[4:7]
	v_mfma_f32_16x16x32_bf16 v[0:3], v[178:181], v[210:213], v[0:3]
	s_setprio 0
	s_barrier
	s_add_i32 s53, 0, 0x18000
	s_add_i32 s54, 0, 0x1c000
	v_add_u32_e32 v162, s53, v153
	v_add_u32_e32 v178, s54, v153
	ds_read_b128 v[144:147], v162
	ds_read_b128 v[148:151], v162 offset:1024
	ds_read_b128 v[158:161], v162 offset:2048
	ds_read_b128 v[162:165], v162 offset:3072
	ds_read_b128 v[166:169], v178
	ds_read_b128 v[170:173], v178 offset:1024
	ds_read_b128 v[174:177], v178 offset:2048
	ds_read_b128 v[178:181], v178 offset:3072
	s_add_u32 s18, s24, 0xb0000
	s_addc_u32 s19, s25, 0
	s_mov_b32 m0, s31
	ds_read_b128 v[182:185], v157 offset:32768
	ds_read_b128 v[186:189], v157 offset:33792
	ds_read_b128 v[190:193], v157 offset:34816
	ds_read_b128 v[194:197], v157 offset:35840
	ds_read_b128 v[198:201], v157 offset:36864
	ds_read_b128 v[202:205], v157 offset:37888
	ds_read_b128 v[206:209], v157 offset:38912
	ds_read_b128 v[210:213], v157 offset:39936
	global_load_lds_dwordx4 v134, s[18:19]
	s_mov_b32 m0, s33
	s_nop 0
	global_load_lds_dwordx4 v130, s[18:19]
	s_waitcnt vmcnt(8)
	s_waitcnt lgkmcnt(0)
	s_barrier
	s_setprio 1
	s_waitcnt lgkmcnt(0)
	v_mfma_f32_16x16x32_bf16 v[124:127], v[144:147], v[182:185], v[124:127]
	v_mfma_f32_16x16x32_bf16 v[120:123], v[158:161], v[182:185], v[120:123]
	v_mfma_f32_16x16x32_bf16 v[112:115], v[144:147], v[190:193], v[112:115]
	v_mfma_f32_16x16x32_bf16 v[108:111], v[158:161], v[190:193], v[108:111]
	v_mfma_f32_16x16x32_bf16 v[96:99], v[144:147], v[198:201], v[96:99]
	v_mfma_f32_16x16x32_bf16 v[92:95], v[158:161], v[198:201], v[92:95]
	v_mfma_f32_16x16x32_bf16 v[80:83], v[144:147], v[206:209], v[80:83]
	v_mfma_f32_16x16x32_bf16 v[76:79], v[158:161], v[206:209], v[76:79]
	v_mfma_f32_16x16x32_bf16 v[124:127], v[148:151], v[186:189], v[124:127]
	v_mfma_f32_16x16x32_bf16 v[120:123], v[162:165], v[186:189], v[120:123]
	v_mfma_f32_16x16x32_bf16 v[112:115], v[148:151], v[194:197], v[112:115]
	v_mfma_f32_16x16x32_bf16 v[108:111], v[162:165], v[194:197], v[108:111]
	v_mfma_f32_16x16x32_bf16 v[96:99], v[148:151], v[202:205], v[96:99]
	v_mfma_f32_16x16x32_bf16 v[92:95], v[162:165], v[202:205], v[92:95]
	v_mfma_f32_16x16x32_bf16 v[80:83], v[148:151], v[210:213], v[80:83]
	v_mfma_f32_16x16x32_bf16 v[76:79], v[162:165], v[210:213], v[76:79]
	s_setprio 0
	s_setprio 1
	v_mfma_f32_16x16x32_bf16 v[116:119], v[166:169], v[182:185], v[116:119]
	v_mfma_f32_16x16x32_bf16 v[104:107], v[174:177], v[182:185], v[104:107]
	v_mfma_f32_16x16x32_bf16 v[100:103], v[166:169], v[190:193], v[100:103]
	v_mfma_f32_16x16x32_bf16 v[88:91], v[174:177], v[190:193], v[88:91]
	v_mfma_f32_16x16x32_bf16 v[84:87], v[166:169], v[198:201], v[84:87]
	v_mfma_f32_16x16x32_bf16 v[72:75], v[174:177], v[198:201], v[72:75]
	v_mfma_f32_16x16x32_bf16 v[68:71], v[166:169], v[206:209], v[68:71]
	v_mfma_f32_16x16x32_bf16 v[64:67], v[174:177], v[206:209], v[64:67]
	v_mfma_f32_16x16x32_bf16 v[116:119], v[170:173], v[186:189], v[116:119]
	v_mfma_f32_16x16x32_bf16 v[104:107], v[178:181], v[186:189], v[104:107]
	v_mfma_f32_16x16x32_bf16 v[100:103], v[170:173], v[194:197], v[100:103]
	v_mfma_f32_16x16x32_bf16 v[88:91], v[178:181], v[194:197], v[88:91]
	v_mfma_f32_16x16x32_bf16 v[84:87], v[170:173], v[202:205], v[84:87]
	v_mfma_f32_16x16x32_bf16 v[72:75], v[178:181], v[202:205], v[72:75]
	v_mfma_f32_16x16x32_bf16 v[68:71], v[170:173], v[210:213], v[68:71]
	v_mfma_f32_16x16x32_bf16 v[64:67], v[178:181], v[210:213], v[64:67]
	s_setprio 0
	s_barrier
	s_add_i32 s18, s53, s28
	s_mov_b32 m0, s18
	ds_read_b128 v[182:185], v157 offset:49152
	ds_read_b128 v[186:189], v157 offset:50176
	ds_read_b128 v[190:193], v157 offset:51200
	ds_read_b128 v[194:197], v157 offset:52224
	ds_read_b128 v[198:201], v157 offset:53248
	ds_read_b128 v[202:205], v157 offset:54272
	ds_read_b128 v[206:209], v157 offset:55296
	ds_read_b128 v[210:213], v157 offset:56320
	global_load_lds_dwordx4 v132, s[98:99]
	s_add_i32 m0, s18, 0x2000
	s_add_u32 s18, s22, 0xb0080
	s_addc_u32 s19, s23, 0
	s_add_i32 s22, s54, s28
	global_load_lds_dwordx4 v128, s[98:99]
	s_mov_b32 m0, s22
	s_nop 0
	global_load_lds_dwordx4 v132, s[18:19]
	s_add_i32 m0, s22, 0x2000
	s_nop 0
	global_load_lds_dwordx4 v128, s[18:19]
	s_mov_b32 m0, s37
	s_nop 0
	global_load_lds_dwordx4 v134, s[100:101]
	s_mov_b32 m0, s38
	s_nop 0
	global_load_lds_dwordx4 v130, s[100:101]
	s_waitcnt vmcnt(8)
	s_waitcnt lgkmcnt(0)
	s_barrier
	s_setprio 1
	s_waitcnt lgkmcnt(0)
	v_mfma_f32_16x16x32_bf16 v[60:63], v[144:147], v[182:185], v[60:63]
	v_mfma_f32_16x16x32_bf16 v[56:59], v[158:161], v[182:185], v[56:59]
	v_mfma_f32_16x16x32_bf16 v[48:51], v[144:147], v[190:193], v[48:51]
	v_mfma_f32_16x16x32_bf16 v[44:47], v[158:161], v[190:193], v[44:47]
	v_mfma_f32_16x16x32_bf16 v[32:35], v[144:147], v[198:201], v[32:35]
	v_mfma_f32_16x16x32_bf16 v[28:31], v[158:161], v[198:201], v[28:31]
	v_mfma_f32_16x16x32_bf16 v[16:19], v[144:147], v[206:209], v[16:19]
	v_mfma_f32_16x16x32_bf16 v[12:15], v[158:161], v[206:209], v[12:15]
	v_mfma_f32_16x16x32_bf16 v[60:63], v[148:151], v[186:189], v[60:63]
	v_mfma_f32_16x16x32_bf16 v[56:59], v[162:165], v[186:189], v[56:59]
	v_mfma_f32_16x16x32_bf16 v[48:51], v[148:151], v[194:197], v[48:51]
	v_mfma_f32_16x16x32_bf16 v[44:47], v[162:165], v[194:197], v[44:47]
	v_mfma_f32_16x16x32_bf16 v[32:35], v[148:151], v[202:205], v[32:35]
	v_mfma_f32_16x16x32_bf16 v[28:31], v[162:165], v[202:205], v[28:31]
	v_mfma_f32_16x16x32_bf16 v[16:19], v[148:151], v[210:213], v[16:19]
	v_mfma_f32_16x16x32_bf16 v[12:15], v[162:165], v[210:213], v[12:15]
	s_setprio 0
	s_setprio 1
	v_mfma_f32_16x16x32_bf16 v[52:55], v[166:169], v[182:185], v[52:55]
	v_mfma_f32_16x16x32_bf16 v[40:43], v[174:177], v[182:185], v[40:43]
	v_mfma_f32_16x16x32_bf16 v[36:39], v[166:169], v[190:193], v[36:39]
	v_mfma_f32_16x16x32_bf16 v[24:27], v[174:177], v[190:193], v[24:27]
	v_mfma_f32_16x16x32_bf16 v[20:23], v[166:169], v[198:201], v[20:23]
	v_mfma_f32_16x16x32_bf16 v[8:11], v[174:177], v[198:201], v[8:11]
	v_mfma_f32_16x16x32_bf16 v[4:7], v[166:169], v[206:209], v[4:7]
	v_mfma_f32_16x16x32_bf16 v[0:3], v[174:177], v[206:209], v[0:3]
	v_mfma_f32_16x16x32_bf16 v[52:55], v[170:173], v[186:189], v[52:55]
	v_mfma_f32_16x16x32_bf16 v[40:43], v[178:181], v[186:189], v[40:43]
	v_mfma_f32_16x16x32_bf16 v[36:39], v[170:173], v[194:197], v[36:39]
	v_mfma_f32_16x16x32_bf16 v[24:27], v[178:181], v[194:197], v[24:27]
	v_mfma_f32_16x16x32_bf16 v[20:23], v[170:173], v[202:205], v[20:23]
	v_mfma_f32_16x16x32_bf16 v[8:11], v[178:181], v[202:205], v[8:11]
	v_mfma_f32_16x16x32_bf16 v[4:7], v[170:173], v[210:213], v[4:7]
	v_mfma_f32_16x16x32_bf16 v[0:3], v[178:181], v[210:213], v[0:3]
	s_setprio 0
	s_barrier
	s_add_i32 s52, s52, 2
	s_add_u32 s50, s50, 0x100
	s_addc_u32 s51, s51, 0
	s_cmp_gt_u32 s52, 41
	s_mov_b64 s[18:19], s[20:21]
	s_cbranch_scc0 .LBB0_1124
	s_and_b64 vcc, exec, s[14:15]
	s_cbranch_vccz .LBB0_1127
	s_barrier
